# stack of sync/K-loop micro-edits: pipelined polls + early invalidate, merged two-counter polls, no poll sleeps, redundant K-loop wait and mid setprio pair removed, bias2 rows shifted to early batches
# speedup vs baseline: 1.0114x; 1.0027x over previous
.LBB0_161:
	s_and_b32 s10, s14, 0xff
	s_mov_b64 s[8:9], -1
	s_cmp_lg_u32 s10, 0
	s_mov_b64 s[12:13], -1
	s_cbranch_scc0 .LBB0_164
	s_and_b64 vcc, exec, s[12:13]
	s_cbranch_vccz .LBB0_160

.LBB0_198:
	s_andn2_b64 vcc, exec, s[18:19]
	s_mov_b64 s[18:19], -1
	s_cbranch_vccnz .LBB0_195
	s_and_b32 s12, s3, 0xff
	s_cmp_eq_u32 s12, 0
	s_mov_b64 s[20:21], -1
	s_cbranch_scc0 .LBB0_202
	global_load_dword v1, v0, s[6:7] sc1
	s_waitcnt vmcnt(0)
	v_cmp_eq_u32_e32 vcc, 0, v1
	s_cbranch_vccnz .LBB0_204
	s_mov_b64 s[20:21], 0
	s_mov_b64 s[12:13], -1

.LBB0_228:
	ds_read_b128 v[128:131], v179
	ds_read_b128 v[132:135], v179 offset:1024
	ds_read_b128 v[136:139], v179 offset:2048
	ds_read_b128 v[140:143], v179 offset:3072
	ds_read_b128 v[162:165], v180
	ds_read_b128 v[166:169], v180 offset:1024
	ds_read_b128 v[170:173], v180 offset:2048
	ds_read_b128 v[186:189], v180 offset:3072
	s_add_u32 s8, s6, 0x10000
	s_addc_u32 s9, s7, 0
	s_cmp_eq_u32 s92, 12
	s_cselect_b32 s80, s69, s8
	s_cselect_b32 s81, s18, s9
	s_cselect_b32 s12, s77, vcc_lo
	s_cselect_b32 s13, s71, vcc_hi
	s_add_u32 s10, s80, 0x8000
	s_addc_u32 s11, s81, 0
	s_add_i32 m0, s79, 0xc000
	ds_read_b128 v[190:193], v181
	ds_read_b128 v[194:197], v181 offset:1024
	ds_read_b128 v[198:201], v181 offset:2048
	ds_read_b128 v[202:205], v181 offset:3072
	ds_read_b128 v[206:209], v181 offset:4096
	ds_read_b128 v[210:213], v181 offset:5120
	ds_read_b128 v[214:217], v181 offset:6144
	ds_read_b128 v[218:221], v181 offset:7168
	global_load_lds_dwordx4 v154, s[6:7]
	s_add_i32 m0, s79, 0xe000
	s_nop 0
	global_load_lds_dwordx4 v156, s[6:7]
	s_waitcnt vmcnt(8)
	s_waitcnt lgkmcnt(0)
	s_barrier
	s_setprio 1
	v_mfma_f32_16x16x32_bf16 v[124:127], v[128:131], v[190:193], v[124:127]
	v_mfma_f32_16x16x32_bf16 v[120:123], v[136:139], v[190:193], v[120:123]
	v_mfma_f32_16x16x32_bf16 v[108:111], v[128:131], v[198:201], v[108:111]
	v_mfma_f32_16x16x32_bf16 v[104:107], v[136:139], v[198:201], v[104:107]
	v_mfma_f32_16x16x32_bf16 v[92:95], v[128:131], v[206:209], v[92:95]
	v_mfma_f32_16x16x32_bf16 v[88:91], v[136:139], v[206:209], v[88:91]
	v_mfma_f32_16x16x32_bf16 v[76:79], v[128:131], v[214:217], v[76:79]
	v_mfma_f32_16x16x32_bf16 v[72:75], v[136:139], v[214:217], v[72:75]
	v_mfma_f32_16x16x32_bf16 v[124:127], v[132:135], v[194:197], v[124:127]
	v_mfma_f32_16x16x32_bf16 v[120:123], v[140:143], v[194:197], v[120:123]
	v_mfma_f32_16x16x32_bf16 v[108:111], v[132:135], v[202:205], v[108:111]
	v_mfma_f32_16x16x32_bf16 v[104:107], v[140:143], v[202:205], v[104:107]
	v_mfma_f32_16x16x32_bf16 v[92:95], v[132:135], v[210:213], v[92:95]
	v_mfma_f32_16x16x32_bf16 v[88:91], v[140:143], v[210:213], v[88:91]
	v_mfma_f32_16x16x32_bf16 v[76:79], v[132:135], v[218:221], v[76:79]
	v_mfma_f32_16x16x32_bf16 v[72:75], v[140:143], v[218:221], v[72:75]
	v_mfma_f32_16x16x32_bf16 v[116:119], v[162:165], v[190:193], v[116:119]
	v_mfma_f32_16x16x32_bf16 v[112:115], v[170:173], v[190:193], v[112:115]
	v_mfma_f32_16x16x32_bf16 v[100:103], v[162:165], v[198:201], v[100:103]
	v_mfma_f32_16x16x32_bf16 v[96:99], v[170:173], v[198:201], v[96:99]
	v_mfma_f32_16x16x32_bf16 v[84:87], v[162:165], v[206:209], v[84:87]
	v_mfma_f32_16x16x32_bf16 v[80:83], v[170:173], v[206:209], v[80:83]
	v_mfma_f32_16x16x32_bf16 v[68:71], v[162:165], v[214:217], v[68:71]
	v_mfma_f32_16x16x32_bf16 v[64:67], v[170:173], v[214:217], v[64:67]
	v_mfma_f32_16x16x32_bf16 v[116:119], v[166:169], v[194:197], v[116:119]
	v_mfma_f32_16x16x32_bf16 v[112:115], v[186:189], v[194:197], v[112:115]
	v_mfma_f32_16x16x32_bf16 v[100:103], v[166:169], v[202:205], v[100:103]
	v_mfma_f32_16x16x32_bf16 v[96:99], v[186:189], v[202:205], v[96:99]
	v_mfma_f32_16x16x32_bf16 v[84:87], v[166:169], v[210:213], v[84:87]
	v_mfma_f32_16x16x32_bf16 v[80:83], v[186:189], v[210:213], v[80:83]
	v_mfma_f32_16x16x32_bf16 v[68:71], v[166:169], v[218:221], v[68:71]
	v_mfma_f32_16x16x32_bf16 v[64:67], v[186:189], v[218:221], v[64:67]
	s_setprio 0
	s_barrier
	s_add_i32 s6, s34, s84
	s_mov_b32 m0, s6
	ds_read_b128 v[190:193], v181 offset:16384
	ds_read_b128 v[194:197], v181 offset:17408
	ds_read_b128 v[198:201], v181 offset:18432
	ds_read_b128 v[202:205], v181 offset:19456
	ds_read_b128 v[206:209], v181 offset:20480
	ds_read_b128 v[210:213], v181 offset:21504
	ds_read_b128 v[214:217], v181 offset:22528
	ds_read_b128 v[218:221], v181 offset:23552
	global_load_lds_dwordx4 v146, s[12:13]
	s_add_i32 m0, s6, 0x2000
	s_add_u32 s6, s12, 0x40000
	s_addc_u32 s7, s13, 0
	s_add_i32 s38, s35, s84
	global_load_lds_dwordx4 v150, s[12:13]
	s_mov_b32 m0, s38
	s_nop 0
	global_load_lds_dwordx4 v146, s[6:7]
	s_add_i32 m0, s38, 0x2000
	s_nop 0
	global_load_lds_dwordx4 v150, s[6:7]
	s_mov_b32 m0, s79
	s_nop 0
	global_load_lds_dwordx4 v144, s[80:81]
	s_mov_b32 m0, s85
	s_nop 0
	global_load_lds_dwordx4 v148, s[80:81]
	s_waitcnt vmcnt(8)
	s_waitcnt lgkmcnt(0)
	s_barrier
	s_setprio 1
	v_mfma_f32_16x16x32_bf16 v[60:63], v[128:131], v[190:193], v[60:63]
	v_mfma_f32_16x16x32_bf16 v[56:59], v[136:139], v[190:193], v[56:59]
	v_mfma_f32_16x16x32_bf16 v[44:47], v[128:131], v[198:201], v[44:47]
	v_mfma_f32_16x16x32_bf16 v[40:43], v[136:139], v[198:201], v[40:43]
	v_mfma_f32_16x16x32_bf16 v[28:31], v[128:131], v[206:209], v[28:31]
	v_mfma_f32_16x16x32_bf16 v[24:27], v[136:139], v[206:209], v[24:27]
	v_mfma_f32_16x16x32_bf16 v[12:15], v[128:131], v[214:217], v[12:15]
	v_mfma_f32_16x16x32_bf16 v[8:11], v[136:139], v[214:217], v[8:11]
	v_mfma_f32_16x16x32_bf16 v[60:63], v[132:135], v[194:197], v[60:63]
	v_mfma_f32_16x16x32_bf16 v[56:59], v[140:143], v[194:197], v[56:59]
	v_mfma_f32_16x16x32_bf16 v[44:47], v[132:135], v[202:205], v[44:47]
	v_mfma_f32_16x16x32_bf16 v[40:43], v[140:143], v[202:205], v[40:43]
	v_mfma_f32_16x16x32_bf16 v[28:31], v[132:135], v[210:213], v[28:31]
	v_mfma_f32_16x16x32_bf16 v[24:27], v[140:143], v[210:213], v[24:27]
	v_mfma_f32_16x16x32_bf16 v[12:15], v[132:135], v[218:221], v[12:15]
	v_mfma_f32_16x16x32_bf16 v[8:11], v[140:143], v[218:221], v[8:11]
	v_mfma_f32_16x16x32_bf16 v[52:55], v[162:165], v[190:193], v[52:55]
	v_mfma_f32_16x16x32_bf16 v[48:51], v[170:173], v[190:193], v[48:51]
	v_mfma_f32_16x16x32_bf16 v[36:39], v[162:165], v[198:201], v[36:39]
	v_mfma_f32_16x16x32_bf16 v[32:35], v[170:173], v[198:201], v[32:35]
	v_mfma_f32_16x16x32_bf16 v[20:23], v[162:165], v[206:209], v[20:23]
	v_mfma_f32_16x16x32_bf16 v[16:19], v[170:173], v[206:209], v[16:19]
	v_mfma_f32_16x16x32_bf16 v[4:7], v[162:165], v[214:217], v[4:7]
	v_mfma_f32_16x16x32_bf16 v[0:3], v[170:173], v[214:217], v[0:3]
	v_mfma_f32_16x16x32_bf16 v[52:55], v[166:169], v[194:197], v[52:55]
	v_mfma_f32_16x16x32_bf16 v[48:51], v[186:189], v[194:197], v[48:51]
	v_mfma_f32_16x16x32_bf16 v[36:39], v[166:169], v[202:205], v[36:39]
	v_mfma_f32_16x16x32_bf16 v[32:35], v[186:189], v[202:205], v[32:35]
	v_mfma_f32_16x16x32_bf16 v[20:23], v[166:169], v[210:213], v[20:23]
	v_mfma_f32_16x16x32_bf16 v[16:19], v[186:189], v[210:213], v[16:19]
	v_mfma_f32_16x16x32_bf16 v[4:7], v[166:169], v[218:221], v[4:7]
	v_mfma_f32_16x16x32_bf16 v[0:3], v[186:189], v[218:221], v[0:3]
	s_setprio 0
	s_barrier
	s_add_i32 s38, 0, 0x18000
	s_add_i32 s39, 0, 0x1c000
	v_add_u32_e32 v140, s38, v178
	v_add_u32_e32 v152, s39, v178
	ds_read_b128 v[128:131], v140
	ds_read_b128 v[132:135], v140 offset:1024
	ds_read_b128 v[136:139], v140 offset:2048
	ds_read_b128 v[140:143], v140 offset:3072
	ds_read_b128 v[162:165], v152
	ds_read_b128 v[166:169], v152 offset:1024
	ds_read_b128 v[170:173], v152 offset:2048
	ds_read_b128 v[186:189], v152 offset:3072
	s_add_u32 s6, s80, 0x4000
	s_addc_u32 s7, s81, 0
	s_mov_b32 m0, s86
	ds_read_b128 v[190:193], v181 offset:32768
	ds_read_b128 v[194:197], v181 offset:33792
	ds_read_b128 v[198:201], v181 offset:34816
	ds_read_b128 v[202:205], v181 offset:35840
	ds_read_b128 v[206:209], v181 offset:36864
	ds_read_b128 v[210:213], v181 offset:37888
	ds_read_b128 v[214:217], v181 offset:38912
	ds_read_b128 v[218:221], v181 offset:39936
	global_load_lds_dwordx4 v144, s[6:7]
	s_mov_b32 m0, s87
	s_nop 0
	global_load_lds_dwordx4 v148, s[6:7]
	s_waitcnt vmcnt(8)
	s_waitcnt lgkmcnt(0)
	s_barrier
	s_setprio 1
	v_mfma_f32_16x16x32_bf16 v[124:127], v[128:131], v[190:193], v[124:127]
	v_mfma_f32_16x16x32_bf16 v[120:123], v[136:139], v[190:193], v[120:123]
	v_mfma_f32_16x16x32_bf16 v[108:111], v[128:131], v[198:201], v[108:111]
	v_mfma_f32_16x16x32_bf16 v[104:107], v[136:139], v[198:201], v[104:107]
	v_mfma_f32_16x16x32_bf16 v[92:95], v[128:131], v[206:209], v[92:95]
	v_mfma_f32_16x16x32_bf16 v[88:91], v[136:139], v[206:209], v[88:91]
	v_mfma_f32_16x16x32_bf16 v[76:79], v[128:131], v[214:217], v[76:79]
	v_mfma_f32_16x16x32_bf16 v[72:75], v[136:139], v[214:217], v[72:75]
	v_mfma_f32_16x16x32_bf16 v[124:127], v[132:135], v[194:197], v[124:127]
	v_mfma_f32_16x16x32_bf16 v[120:123], v[140:143], v[194:197], v[120:123]
	v_mfma_f32_16x16x32_bf16 v[108:111], v[132:135], v[202:205], v[108:111]
	v_mfma_f32_16x16x32_bf16 v[104:107], v[140:143], v[202:205], v[104:107]
	v_mfma_f32_16x16x32_bf16 v[92:95], v[132:135], v[210:213], v[92:95]
	v_mfma_f32_16x16x32_bf16 v[88:91], v[140:143], v[210:213], v[88:91]
	v_mfma_f32_16x16x32_bf16 v[76:79], v[132:135], v[218:221], v[76:79]
	v_mfma_f32_16x16x32_bf16 v[72:75], v[140:143], v[218:221], v[72:75]
	v_mfma_f32_16x16x32_bf16 v[116:119], v[162:165], v[190:193], v[116:119]
	v_mfma_f32_16x16x32_bf16 v[112:115], v[170:173], v[190:193], v[112:115]
	v_mfma_f32_16x16x32_bf16 v[100:103], v[162:165], v[198:201], v[100:103]
	v_mfma_f32_16x16x32_bf16 v[96:99], v[170:173], v[198:201], v[96:99]
	v_mfma_f32_16x16x32_bf16 v[84:87], v[162:165], v[206:209], v[84:87]
	v_mfma_f32_16x16x32_bf16 v[80:83], v[170:173], v[206:209], v[80:83]
	v_mfma_f32_16x16x32_bf16 v[68:71], v[162:165], v[214:217], v[68:71]
	v_mfma_f32_16x16x32_bf16 v[64:67], v[170:173], v[214:217], v[64:67]
	v_mfma_f32_16x16x32_bf16 v[116:119], v[166:169], v[194:197], v[116:119]
	v_mfma_f32_16x16x32_bf16 v[112:115], v[186:189], v[194:197], v[112:115]
	v_mfma_f32_16x16x32_bf16 v[100:103], v[166:169], v[202:205], v[100:103]
	v_mfma_f32_16x16x32_bf16 v[96:99], v[186:189], v[202:205], v[96:99]
	v_mfma_f32_16x16x32_bf16 v[84:87], v[166:169], v[210:213], v[84:87]
	v_mfma_f32_16x16x32_bf16 v[80:83], v[186:189], v[210:213], v[80:83]
	v_mfma_f32_16x16x32_bf16 v[68:71], v[166:169], v[218:221], v[68:71]
	v_mfma_f32_16x16x32_bf16 v[64:67], v[186:189], v[218:221], v[64:67]
	s_setprio 0
	s_barrier
	s_add_u32 s98, s12, s48
	s_addc_u32 s99, s13, s49
	s_add_i32 s6, s38, s84
	s_mov_b32 m0, s6
	ds_read_b128 v[190:193], v181 offset:49152
	ds_read_b128 v[194:197], v181 offset:50176
	ds_read_b128 v[198:201], v181 offset:51200
	ds_read_b128 v[202:205], v181 offset:52224
	ds_read_b128 v[206:209], v181 offset:53248
	ds_read_b128 v[210:213], v181 offset:54272
	ds_read_b128 v[214:217], v181 offset:55296
	ds_read_b128 v[218:221], v181 offset:56320
	global_load_lds_dwordx4 v146, s[98:99]
	s_add_i32 m0, s6, 0x2000
	s_add_u32 s6, s12, 0x40080
	s_addc_u32 s7, s13, 0
	s_add_i32 s12, s39, s84
	global_load_lds_dwordx4 v150, s[98:99]
	s_mov_b32 m0, s12
	s_nop 0
	global_load_lds_dwordx4 v146, s[6:7]
	s_add_i32 m0, s12, 0x2000
	s_nop 0
	global_load_lds_dwordx4 v150, s[6:7]
	s_mov_b32 m0, s33
	s_nop 0
	global_load_lds_dwordx4 v144, s[10:11]
	s_mov_b32 m0, s56
	s_nop 0
	global_load_lds_dwordx4 v148, s[10:11]
	s_waitcnt vmcnt(8)
	s_waitcnt lgkmcnt(0)
	s_barrier
	s_setprio 1
	v_mfma_f32_16x16x32_bf16 v[60:63], v[128:131], v[190:193], v[60:63]
	v_mfma_f32_16x16x32_bf16 v[56:59], v[136:139], v[190:193], v[56:59]
	v_mfma_f32_16x16x32_bf16 v[44:47], v[128:131], v[198:201], v[44:47]
	v_mfma_f32_16x16x32_bf16 v[40:43], v[136:139], v[198:201], v[40:43]
	v_mfma_f32_16x16x32_bf16 v[28:31], v[128:131], v[206:209], v[28:31]
	v_mfma_f32_16x16x32_bf16 v[24:27], v[136:139], v[206:209], v[24:27]
	v_mfma_f32_16x16x32_bf16 v[12:15], v[128:131], v[214:217], v[12:15]
	v_mfma_f32_16x16x32_bf16 v[8:11], v[136:139], v[214:217], v[8:11]
	v_mfma_f32_16x16x32_bf16 v[60:63], v[132:135], v[194:197], v[60:63]
	v_mfma_f32_16x16x32_bf16 v[56:59], v[140:143], v[194:197], v[56:59]
	v_mfma_f32_16x16x32_bf16 v[44:47], v[132:135], v[202:205], v[44:47]
	v_mfma_f32_16x16x32_bf16 v[40:43], v[140:143], v[202:205], v[40:43]
	v_mfma_f32_16x16x32_bf16 v[28:31], v[132:135], v[210:213], v[28:31]
	v_mfma_f32_16x16x32_bf16 v[24:27], v[140:143], v[210:213], v[24:27]
	v_mfma_f32_16x16x32_bf16 v[12:15], v[132:135], v[218:221], v[12:15]
	v_mfma_f32_16x16x32_bf16 v[8:11], v[140:143], v[218:221], v[8:11]
	v_mfma_f32_16x16x32_bf16 v[52:55], v[162:165], v[190:193], v[52:55]
	v_mfma_f32_16x16x32_bf16 v[48:51], v[170:173], v[190:193], v[48:51]
	v_mfma_f32_16x16x32_bf16 v[36:39], v[162:165], v[198:201], v[36:39]
	v_mfma_f32_16x16x32_bf16 v[32:35], v[170:173], v[198:201], v[32:35]
	v_mfma_f32_16x16x32_bf16 v[20:23], v[162:165], v[206:209], v[20:23]
	v_mfma_f32_16x16x32_bf16 v[16:19], v[170:173], v[206:209], v[16:19]
	v_mfma_f32_16x16x32_bf16 v[4:7], v[162:165], v[214:217], v[4:7]
	v_mfma_f32_16x16x32_bf16 v[0:3], v[170:173], v[214:217], v[0:3]
	v_mfma_f32_16x16x32_bf16 v[52:55], v[166:169], v[194:197], v[52:55]
	v_mfma_f32_16x16x32_bf16 v[48:51], v[186:189], v[194:197], v[48:51]
	v_mfma_f32_16x16x32_bf16 v[36:39], v[166:169], v[202:205], v[36:39]
	v_mfma_f32_16x16x32_bf16 v[32:35], v[186:189], v[202:205], v[32:35]
	v_mfma_f32_16x16x32_bf16 v[20:23], v[166:169], v[210:213], v[20:23]
	v_mfma_f32_16x16x32_bf16 v[16:19], v[186:189], v[210:213], v[16:19]
	v_mfma_f32_16x16x32_bf16 v[4:7], v[166:169], v[218:221], v[4:7]
	v_mfma_f32_16x16x32_bf16 v[0:3], v[186:189], v[218:221], v[0:3]
	s_setprio 0
	s_barrier
	s_add_i32 s92, s92, 2
	s_add_u32 vcc_lo, vcc_lo, 0x100
	s_addc_u32 vcc_hi, vcc_hi, 0
	s_cmp_gt_u32 s92, 13
	s_mov_b64 s[6:7], s[8:9]
	s_cbranch_scc0 .LBB0_228
	s_and_b64 vcc, exec, s[82:83]
	s_cbranch_vccz .LBB0_231
	s_barrier

.LBB0_304:
	s_and_b64 vcc, exec, s[20:21]
	s_mov_b64 s[20:21], -1
	s_cbranch_vccz .LBB0_300
	s_and_b32 s15, s14, 0xff
	s_cmp_eq_u32 s15, 0
	s_mov_b64 s[22:23], -1
	s_cbranch_scc0 .LBB0_308
	global_load_dword v1, v0, s[30:31] sc1
	s_waitcnt vmcnt(0)
	v_cmp_eq_u32_e32 vcc, 0, v1
	s_cbranch_vccnz .LBB0_311
	s_mov_b64 s[22:23], 0
	s_mov_b64 s[18:19], -1

.LBB0_329:
	s_and_b32 s46, s66, 0xff
	s_mov_b64 s[44:45], -1
	s_cmp_lg_u32 s46, 0
	s_mov_b64 s[48:49], -1
	s_cbranch_scc0 .LBB0_332
	s_and_b64 vcc, exec, s[48:49]
	s_cbranch_vccz .LBB0_328

.LBB0_364:
	s_and_b32 s42, s46, 0xff
	s_mov_b64 s[16:17], -1
	s_cmp_lg_u32 s42, 0
	s_mov_b64 s[44:45], -1
	s_cbranch_scc0 .LBB0_367
	s_and_b64 vcc, exec, s[44:45]
	s_cbranch_vccz .LBB0_363

.LBB0_385:
	s_and_b32 s22, s46, 0xff
	s_mov_b64 s[20:21], -1
	s_cmp_lg_u32 s22, 0
	s_mov_b64 s[26:27], -1
	s_cbranch_scc0 .LBB0_388
	s_and_b64 vcc, exec, s[26:27]
	s_cbranch_vccz .LBB0_384

.LBB0_422:
	s_and_b32 s8, s14, 0xff
	s_mov_b64 s[6:7], -1
	s_cmp_lg_u32 s8, 0
	s_mov_b64 s[10:11], -1
	s_cbranch_scc0 .LBB0_425
	s_and_b64 vcc, exec, s[10:11]
	s_cbranch_vccz .LBB0_421

.LBB0_448:
	v_add_u32_e32 v1, s78, v210
	ds_read_b128 v[132:135], v1
	ds_read_b128 v[136:139], v1 offset:1024
	ds_read_b128 v[140:143], v1 offset:2048
	ds_read_b128 v[144:147], v1 offset:3072
	v_add_u32_e32 v1, s79, v210
	s_add_u32 s48, s38, s46
	ds_read_b128 v[148:151], v1
	ds_read_b128 v[152:155], v1 offset:1024
	ds_read_b128 v[156:159], v1 offset:2048
	ds_read_b128 v[160:163], v1 offset:3072
	s_addc_u32 s49, s39, s47
	s_add_u32 s48, s48, 0x10000
	s_addc_u32 s49, s49, 0
	s_cmp_eq_u32 s46, 0xf0000
	s_cselect_b32 s64, s81, s48
	s_cselect_b32 s65, s21, s49
	s_cselect_b32 s50, s83, s41
	s_cselect_b32 s51, s19, s86
	s_add_u32 s48, s64, 0x8000
	s_addc_u32 s49, s65, 0
	v_lshl_add_u64 v[2:3], v[204:205], 0, s[46:47]
	s_add_i32 m0, s35, 0xc000
	ds_read_b128 v[164:167], v211
	ds_read_b128 v[168:171], v211 offset:1024
	ds_read_b128 v[172:175], v211 offset:2048
	ds_read_b128 v[176:179], v211 offset:3072
	ds_read_b128 v[180:183], v211 offset:4096
	ds_read_b128 v[184:187], v211 offset:5120
	ds_read_b128 v[212:215], v211 offset:6144
	ds_read_b128 v[216:219], v211 offset:7168
	global_load_lds_dwordx4 v[2:3], off
	v_lshl_add_u64 v[2:3], v[206:207], 0, s[46:47]
	s_add_i32 m0, s35, 0xe000
	s_nop 0
	global_load_lds_dwordx4 v[2:3], off
	s_waitcnt vmcnt(8)
	s_waitcnt lgkmcnt(0)
	s_barrier
	s_setprio 1
	v_mfma_f32_16x16x32_bf16 v[128:131], v[132:135], v[164:167], v[128:131]
	v_mfma_f32_16x16x32_bf16 v[124:127], v[140:143], v[164:167], v[124:127]
	v_mfma_f32_16x16x32_bf16 v[112:115], v[132:135], v[172:175], v[112:115]
	v_mfma_f32_16x16x32_bf16 v[108:111], v[140:143], v[172:175], v[108:111]
	v_mfma_f32_16x16x32_bf16 v[96:99], v[132:135], v[180:183], v[96:99]
	v_mfma_f32_16x16x32_bf16 v[92:95], v[140:143], v[180:183], v[92:95]
	v_mfma_f32_16x16x32_bf16 v[80:83], v[132:135], v[212:215], v[80:83]
	v_mfma_f32_16x16x32_bf16 v[76:79], v[140:143], v[212:215], v[76:79]
	v_mfma_f32_16x16x32_bf16 v[128:131], v[136:139], v[168:171], v[128:131]
	v_mfma_f32_16x16x32_bf16 v[124:127], v[144:147], v[168:171], v[124:127]
	v_mfma_f32_16x16x32_bf16 v[112:115], v[136:139], v[176:179], v[112:115]
	v_mfma_f32_16x16x32_bf16 v[108:111], v[144:147], v[176:179], v[108:111]
	v_mfma_f32_16x16x32_bf16 v[96:99], v[136:139], v[184:187], v[96:99]
	v_mfma_f32_16x16x32_bf16 v[92:95], v[144:147], v[184:187], v[92:95]
	v_mfma_f32_16x16x32_bf16 v[80:83], v[136:139], v[216:219], v[80:83]
	v_mfma_f32_16x16x32_bf16 v[76:79], v[144:147], v[216:219], v[76:79]
	v_mfma_f32_16x16x32_bf16 v[120:123], v[148:151], v[164:167], v[120:123]
	v_mfma_f32_16x16x32_bf16 v[116:119], v[156:159], v[164:167], v[116:119]
	v_mfma_f32_16x16x32_bf16 v[104:107], v[148:151], v[172:175], v[104:107]
	v_mfma_f32_16x16x32_bf16 v[100:103], v[156:159], v[172:175], v[100:103]
	v_mfma_f32_16x16x32_bf16 v[88:91], v[148:151], v[180:183], v[88:91]
	v_mfma_f32_16x16x32_bf16 v[84:87], v[156:159], v[180:183], v[84:87]
	v_mfma_f32_16x16x32_bf16 v[72:75], v[148:151], v[212:215], v[72:75]
	v_mfma_f32_16x16x32_bf16 v[68:71], v[156:159], v[212:215], v[68:71]
	v_mfma_f32_16x16x32_bf16 v[120:123], v[152:155], v[168:171], v[120:123]
	v_mfma_f32_16x16x32_bf16 v[116:119], v[160:163], v[168:171], v[116:119]
	v_mfma_f32_16x16x32_bf16 v[104:107], v[152:155], v[176:179], v[104:107]
	v_mfma_f32_16x16x32_bf16 v[100:103], v[160:163], v[176:179], v[100:103]
	v_mfma_f32_16x16x32_bf16 v[88:91], v[152:155], v[184:187], v[88:91]
	v_mfma_f32_16x16x32_bf16 v[84:87], v[160:163], v[184:187], v[84:87]
	v_mfma_f32_16x16x32_bf16 v[72:75], v[152:155], v[216:219], v[72:75]
	v_mfma_f32_16x16x32_bf16 v[68:71], v[160:163], v[216:219], v[68:71]
	s_setprio 0
	s_barrier
	s_add_i32 s88, s78, s34
	s_mov_b32 m0, s88
	ds_read_b128 v[164:167], v211 offset:16384
	ds_read_b128 v[168:171], v211 offset:17408
	ds_read_b128 v[172:175], v211 offset:18432
	ds_read_b128 v[176:179], v211 offset:19456
	ds_read_b128 v[180:183], v211 offset:20480
	ds_read_b128 v[184:187], v211 offset:21504
	ds_read_b128 v[212:215], v211 offset:22528
	ds_read_b128 v[216:219], v211 offset:23552
	global_load_lds_dwordx4 v192, s[50:51]
	s_add_i32 m0, s88, 0x2000
	s_add_u32 s88, s50, 0x80000
	v_lshl_add_u64 v[222:223], s[50:51], 0, v[188:189]
	s_addc_u32 s89, s51, 0
	s_add_i32 s90, s79, s34
	global_load_lds_dwordx4 v[222:223], off
	s_mov_b32 m0, s90
	s_nop 0
	global_load_lds_dwordx4 v192, s[88:89]
	s_add_i32 m0, s90, 0x2000
	s_nop 0
	global_load_lds_dwordx4 v188, s[88:89]
	s_mov_b32 m0, s35
	s_nop 0
	global_load_lds_dwordx4 v194, s[64:65]
	s_mov_b32 m0, s56
	s_nop 0
	global_load_lds_dwordx4 v190, s[64:65]
	s_waitcnt vmcnt(8)
	s_waitcnt lgkmcnt(0)
	s_barrier
	s_setprio 1
	v_mfma_f32_16x16x32_bf16 v[64:67], v[132:135], v[164:167], v[64:67]
	v_mfma_f32_16x16x32_bf16 v[60:63], v[140:143], v[164:167], v[60:63]
	v_mfma_f32_16x16x32_bf16 v[48:51], v[132:135], v[172:175], v[48:51]
	v_mfma_f32_16x16x32_bf16 v[44:47], v[140:143], v[172:175], v[44:47]
	v_mfma_f32_16x16x32_bf16 v[32:35], v[132:135], v[180:183], v[32:35]
	v_mfma_f32_16x16x32_bf16 v[28:31], v[140:143], v[180:183], v[28:31]
	v_mfma_f32_16x16x32_bf16 v[16:19], v[132:135], v[212:215], v[16:19]
	v_mfma_f32_16x16x32_bf16 v[12:15], v[140:143], v[212:215], v[12:15]
	v_mfma_f32_16x16x32_bf16 v[64:67], v[136:139], v[168:171], v[64:67]
	v_mfma_f32_16x16x32_bf16 v[60:63], v[144:147], v[168:171], v[60:63]
	v_mfma_f32_16x16x32_bf16 v[48:51], v[136:139], v[176:179], v[48:51]
	v_mfma_f32_16x16x32_bf16 v[44:47], v[144:147], v[176:179], v[44:47]
	v_mfma_f32_16x16x32_bf16 v[32:35], v[136:139], v[184:187], v[32:35]
	v_mfma_f32_16x16x32_bf16 v[28:31], v[144:147], v[184:187], v[28:31]
	v_mfma_f32_16x16x32_bf16 v[16:19], v[136:139], v[216:219], v[16:19]
	v_mfma_f32_16x16x32_bf16 v[12:15], v[144:147], v[216:219], v[12:15]
	v_mfma_f32_16x16x32_bf16 v[56:59], v[148:151], v[164:167], v[56:59]
	v_mfma_f32_16x16x32_bf16 v[52:55], v[156:159], v[164:167], v[52:55]
	v_mfma_f32_16x16x32_bf16 v[40:43], v[148:151], v[172:175], v[40:43]
	v_mfma_f32_16x16x32_bf16 v[36:39], v[156:159], v[172:175], v[36:39]
	v_mfma_f32_16x16x32_bf16 v[24:27], v[148:151], v[180:183], v[24:27]
	v_mfma_f32_16x16x32_bf16 v[20:23], v[156:159], v[180:183], v[20:23]
	v_mfma_f32_16x16x32_bf16 v[8:11], v[148:151], v[212:215], v[8:11]
	v_mfma_f32_16x16x32_bf16 v[2:5], v[156:159], v[212:215], v[4:7]
	v_mfma_f32_16x16x32_bf16 v[56:59], v[152:155], v[168:171], v[56:59]
	v_mfma_f32_16x16x32_bf16 v[52:55], v[160:163], v[168:171], v[52:55]
	v_mfma_f32_16x16x32_bf16 v[40:43], v[152:155], v[176:179], v[40:43]
	v_mfma_f32_16x16x32_bf16 v[36:39], v[160:163], v[176:179], v[36:39]
	v_mfma_f32_16x16x32_bf16 v[24:27], v[152:155], v[184:187], v[24:27]
	v_mfma_f32_16x16x32_bf16 v[20:23], v[160:163], v[184:187], v[20:23]
	v_mfma_f32_16x16x32_bf16 v[8:11], v[152:155], v[216:219], v[8:11]
	v_mfma_f32_16x16x32_bf16 v[2:5], v[160:163], v[216:219], v[2:5]
	s_setprio 0
	s_barrier
	s_add_i32 s88, 0, 0x18000
	v_add_u32_e32 v1, s88, v210
	s_add_i32 s89, 0, 0x1c000
	ds_read_b128 v[132:135], v1
	ds_read_b128 v[136:139], v1 offset:1024
	ds_read_b128 v[140:143], v1 offset:2048
	ds_read_b128 v[144:147], v1 offset:3072
	v_add_u32_e32 v1, s89, v210
	ds_read_b128 v[148:151], v1
	ds_read_b128 v[152:155], v1 offset:1024
	ds_read_b128 v[156:159], v1 offset:2048
	ds_read_b128 v[160:163], v1 offset:3072
	s_add_u32 s64, s64, 0x2000
	s_addc_u32 s65, s65, 0
	s_mov_b32 m0, s57
	ds_read_b128 v[164:167], v211 offset:32768
	ds_read_b128 v[168:171], v211 offset:33792
	ds_read_b128 v[172:175], v211 offset:34816
	ds_read_b128 v[176:179], v211 offset:35840
	ds_read_b128 v[180:183], v211 offset:36864
	ds_read_b128 v[184:187], v211 offset:37888
	ds_read_b128 v[212:215], v211 offset:38912
	ds_read_b128 v[216:219], v211 offset:39936
	global_load_lds_dwordx4 v194, s[64:65]
	s_mov_b32 m0, s59
	s_nop 0
	global_load_lds_dwordx4 v190, s[64:65]
	s_waitcnt vmcnt(8)
	s_waitcnt lgkmcnt(0)
	s_barrier
	s_setprio 1
	v_mfma_f32_16x16x32_bf16 v[128:131], v[132:135], v[164:167], v[128:131]
	v_mfma_f32_16x16x32_bf16 v[124:127], v[140:143], v[164:167], v[124:127]
	v_mfma_f32_16x16x32_bf16 v[112:115], v[132:135], v[172:175], v[112:115]
	v_mfma_f32_16x16x32_bf16 v[108:111], v[140:143], v[172:175], v[108:111]
	v_mfma_f32_16x16x32_bf16 v[96:99], v[132:135], v[180:183], v[96:99]
	v_mfma_f32_16x16x32_bf16 v[92:95], v[140:143], v[180:183], v[92:95]
	v_mfma_f32_16x16x32_bf16 v[80:83], v[132:135], v[212:215], v[80:83]
	v_mfma_f32_16x16x32_bf16 v[76:79], v[140:143], v[212:215], v[76:79]
	v_mfma_f32_16x16x32_bf16 v[128:131], v[136:139], v[168:171], v[128:131]
	v_mfma_f32_16x16x32_bf16 v[124:127], v[144:147], v[168:171], v[124:127]
	v_mfma_f32_16x16x32_bf16 v[112:115], v[136:139], v[176:179], v[112:115]
	v_mfma_f32_16x16x32_bf16 v[108:111], v[144:147], v[176:179], v[108:111]
	v_mfma_f32_16x16x32_bf16 v[96:99], v[136:139], v[184:187], v[96:99]
	v_mfma_f32_16x16x32_bf16 v[92:95], v[144:147], v[184:187], v[92:95]
	v_mfma_f32_16x16x32_bf16 v[80:83], v[136:139], v[216:219], v[80:83]
	v_mfma_f32_16x16x32_bf16 v[76:79], v[144:147], v[216:219], v[76:79]
	v_mfma_f32_16x16x32_bf16 v[120:123], v[148:151], v[164:167], v[120:123]
	v_mfma_f32_16x16x32_bf16 v[116:119], v[156:159], v[164:167], v[116:119]
	v_mfma_f32_16x16x32_bf16 v[104:107], v[148:151], v[172:175], v[104:107]
	v_mfma_f32_16x16x32_bf16 v[100:103], v[156:159], v[172:175], v[100:103]
	v_mfma_f32_16x16x32_bf16 v[88:91], v[148:151], v[180:183], v[88:91]
	v_mfma_f32_16x16x32_bf16 v[84:87], v[156:159], v[180:183], v[84:87]
	v_mfma_f32_16x16x32_bf16 v[72:75], v[148:151], v[212:215], v[72:75]
	v_mfma_f32_16x16x32_bf16 v[68:71], v[156:159], v[212:215], v[68:71]
	v_mfma_f32_16x16x32_bf16 v[120:123], v[152:155], v[168:171], v[120:123]
	v_mfma_f32_16x16x32_bf16 v[116:119], v[160:163], v[168:171], v[116:119]
	v_mfma_f32_16x16x32_bf16 v[104:107], v[152:155], v[176:179], v[104:107]
	v_mfma_f32_16x16x32_bf16 v[100:103], v[160:163], v[176:179], v[100:103]
	v_mfma_f32_16x16x32_bf16 v[88:91], v[152:155], v[184:187], v[88:91]
	v_mfma_f32_16x16x32_bf16 v[84:87], v[160:163], v[184:187], v[84:87]
	v_mfma_f32_16x16x32_bf16 v[72:75], v[152:155], v[216:219], v[72:75]
	v_mfma_f32_16x16x32_bf16 v[68:71], v[160:163], v[216:219], v[68:71]
	s_setprio 0
	s_barrier
	s_add_u32 s98, s50, s10
	s_addc_u32 s99, s51, s11
	s_add_i32 s64, s88, s34
	s_mov_b32 m0, s64
	ds_read_b128 v[164:167], v211 offset:49152
	ds_read_b128 v[168:171], v211 offset:50176
	ds_read_b128 v[172:175], v211 offset:51200
	ds_read_b128 v[176:179], v211 offset:52224
	ds_read_b128 v[180:183], v211 offset:53248
	ds_read_b128 v[184:187], v211 offset:54272
	ds_read_b128 v[212:215], v211 offset:55296
	ds_read_b128 v[216:219], v211 offset:56320
	global_load_lds_dwordx4 v192, s[98:99]
	s_add_i32 m0, s64, 0x2000
	s_add_u32 s50, s50, 0x80080
	v_lshl_add_u64 v[6:7], v[222:223], 0, s[10:11]
	s_addc_u32 s51, s51, 0
	s_add_i32 s64, s89, s34
	global_load_lds_dwordx4 v[6:7], off
	s_mov_b32 m0, s64
	s_nop 0
	global_load_lds_dwordx4 v192, s[50:51]
	s_add_i32 m0, s64, 0x2000
	s_nop 0
	global_load_lds_dwordx4 v188, s[50:51]
	s_mov_b32 m0, s74
	s_nop 0
	global_load_lds_dwordx4 v194, s[48:49]
	s_mov_b32 m0, s75
	s_nop 0
	global_load_lds_dwordx4 v190, s[48:49]
	s_waitcnt vmcnt(8)
	s_waitcnt lgkmcnt(0)
	s_barrier
	s_setprio 1
	v_mfma_f32_16x16x32_bf16 v[64:67], v[132:135], v[164:167], v[64:67]
	v_mfma_f32_16x16x32_bf16 v[60:63], v[140:143], v[164:167], v[60:63]
	v_mfma_f32_16x16x32_bf16 v[48:51], v[132:135], v[172:175], v[48:51]
	v_mfma_f32_16x16x32_bf16 v[44:47], v[140:143], v[172:175], v[44:47]
	v_mfma_f32_16x16x32_bf16 v[32:35], v[132:135], v[180:183], v[32:35]
	v_mfma_f32_16x16x32_bf16 v[28:31], v[140:143], v[180:183], v[28:31]
	v_mfma_f32_16x16x32_bf16 v[16:19], v[132:135], v[212:215], v[16:19]
	v_mfma_f32_16x16x32_bf16 v[12:15], v[140:143], v[212:215], v[12:15]
	v_mfma_f32_16x16x32_bf16 v[64:67], v[136:139], v[168:171], v[64:67]
	v_mfma_f32_16x16x32_bf16 v[60:63], v[144:147], v[168:171], v[60:63]
	v_mfma_f32_16x16x32_bf16 v[48:51], v[136:139], v[176:179], v[48:51]
	v_mfma_f32_16x16x32_bf16 v[44:47], v[144:147], v[176:179], v[44:47]
	v_mfma_f32_16x16x32_bf16 v[32:35], v[136:139], v[184:187], v[32:35]
	v_mfma_f32_16x16x32_bf16 v[28:31], v[144:147], v[184:187], v[28:31]
	v_mfma_f32_16x16x32_bf16 v[16:19], v[136:139], v[216:219], v[16:19]
	v_mfma_f32_16x16x32_bf16 v[12:15], v[144:147], v[216:219], v[12:15]
	v_mfma_f32_16x16x32_bf16 v[56:59], v[148:151], v[164:167], v[56:59]
	v_mfma_f32_16x16x32_bf16 v[52:55], v[156:159], v[164:167], v[52:55]
	v_mfma_f32_16x16x32_bf16 v[40:43], v[148:151], v[172:175], v[40:43]
	v_mfma_f32_16x16x32_bf16 v[36:39], v[156:159], v[172:175], v[36:39]
	v_mfma_f32_16x16x32_bf16 v[24:27], v[148:151], v[180:183], v[24:27]
	v_mfma_f32_16x16x32_bf16 v[20:23], v[156:159], v[180:183], v[20:23]
	v_mfma_f32_16x16x32_bf16 v[6:9], v[148:151], v[212:215], v[8:11]
	v_mfma_f32_16x16x32_bf16 v[2:5], v[156:159], v[212:215], v[2:5]
	v_mfma_f32_16x16x32_bf16 v[56:59], v[152:155], v[168:171], v[56:59]
	v_mfma_f32_16x16x32_bf16 v[52:55], v[160:163], v[168:171], v[52:55]
	v_mfma_f32_16x16x32_bf16 v[40:43], v[152:155], v[176:179], v[40:43]
	v_mfma_f32_16x16x32_bf16 v[36:39], v[160:163], v[176:179], v[36:39]
	v_mfma_f32_16x16x32_bf16 v[24:27], v[152:155], v[184:187], v[24:27]
	v_mfma_f32_16x16x32_bf16 v[20:23], v[160:163], v[184:187], v[20:23]
	v_mfma_f32_16x16x32_bf16 v[8:11], v[152:155], v[216:219], v[6:9]
	v_mfma_f32_16x16x32_bf16 v[4:7], v[160:163], v[216:219], v[2:5]
	s_setprio 0
	s_barrier
	s_add_i32 s87, s87, 2
	s_add_u32 s41, s41, 0x100
	s_addc_u32 s86, s86, 0
	s_add_u32 s46, s46, 0x10000
	s_addc_u32 s47, s47, 0
	s_cmp_gt_u32 s87, 29
	s_cbranch_scc1 .LBB0_440

.LBB0_464:
	s_and_b32 s15, s14, 0xff
	s_mov_b64 s[12:13], -1
	s_cmp_lg_u32 s15, 0
	s_mov_b64 s[18:19], -1
	s_cbranch_scc0 .LBB0_467
	s_and_b64 vcc, exec, s[18:19]
	s_cbranch_vccz .LBB0_463

.LBB0_507:
	ds_read_b128 v[128:131], v229
	ds_read_b128 v[132:135], v229 offset:1024
	ds_read_b128 v[136:139], v229 offset:2048
	ds_read_b128 v[140:143], v229 offset:3072
	ds_read_b128 v[144:147], v230
	ds_read_b128 v[148:151], v230 offset:1024
	ds_read_b128 v[152:155], v230 offset:2048
	ds_read_b128 v[156:159], v230 offset:3072
	s_add_u32 s44, s42, 0x10000
	s_addc_u32 s45, s43, 0
	s_cmp_eq_u32 s83, 12
	s_cselect_b32 s50, s21, s44
	s_cselect_b32 s51, s8, s45
	s_cselect_b32 s48, s29, s80
	s_cselect_b32 s49, s27, s81
	s_add_u32 s46, s50, 0x8000
	s_addc_u32 s47, s51, 0
	s_add_i32 m0, s23, 0xc000
	ds_read_b128 v[160:163], v231
	ds_read_b128 v[164:167], v231 offset:1024
	ds_read_b128 v[168:171], v231 offset:2048
	ds_read_b128 v[172:175], v231 offset:3072
	ds_read_b128 v[176:179], v231 offset:4096
	ds_read_b128 v[180:183], v231 offset:5120
	ds_read_b128 v[184:187], v231 offset:6144
	ds_read_b128 v[188:191], v231 offset:7168
	global_load_lds_dwordx4 v200, s[42:43]
	s_add_i32 m0, s23, 0xe000
	s_nop 0
	global_load_lds_dwordx4 v202, s[42:43]
	s_waitcnt vmcnt(8)
	s_waitcnt lgkmcnt(0)
	s_barrier
	s_setprio 1
	v_mfma_f32_16x16x32_bf16 v[124:127], v[128:131], v[160:163], v[124:127]
	v_mfma_f32_16x16x32_bf16 v[120:123], v[136:139], v[160:163], v[120:123]
	v_mfma_f32_16x16x32_bf16 v[108:111], v[128:131], v[168:171], v[108:111]
	v_mfma_f32_16x16x32_bf16 v[104:107], v[136:139], v[168:171], v[104:107]
	v_mfma_f32_16x16x32_bf16 v[92:95], v[128:131], v[176:179], v[92:95]
	v_mfma_f32_16x16x32_bf16 v[88:91], v[136:139], v[176:179], v[88:91]
	v_mfma_f32_16x16x32_bf16 v[76:79], v[128:131], v[184:187], v[76:79]
	v_mfma_f32_16x16x32_bf16 v[72:75], v[136:139], v[184:187], v[72:75]
	v_mfma_f32_16x16x32_bf16 v[124:127], v[132:135], v[164:167], v[124:127]
	v_mfma_f32_16x16x32_bf16 v[120:123], v[140:143], v[164:167], v[120:123]
	v_mfma_f32_16x16x32_bf16 v[108:111], v[132:135], v[172:175], v[108:111]
	v_mfma_f32_16x16x32_bf16 v[104:107], v[140:143], v[172:175], v[104:107]
	v_mfma_f32_16x16x32_bf16 v[92:95], v[132:135], v[180:183], v[92:95]
	v_mfma_f32_16x16x32_bf16 v[88:91], v[140:143], v[180:183], v[88:91]
	v_mfma_f32_16x16x32_bf16 v[76:79], v[132:135], v[188:191], v[76:79]
	v_mfma_f32_16x16x32_bf16 v[72:75], v[140:143], v[188:191], v[72:75]
	v_mfma_f32_16x16x32_bf16 v[116:119], v[144:147], v[160:163], v[116:119]
	v_mfma_f32_16x16x32_bf16 v[112:115], v[152:155], v[160:163], v[112:115]
	v_mfma_f32_16x16x32_bf16 v[100:103], v[144:147], v[168:171], v[100:103]
	v_mfma_f32_16x16x32_bf16 v[96:99], v[152:155], v[168:171], v[96:99]
	v_mfma_f32_16x16x32_bf16 v[84:87], v[144:147], v[176:179], v[84:87]
	v_mfma_f32_16x16x32_bf16 v[80:83], v[152:155], v[176:179], v[80:83]
	v_mfma_f32_16x16x32_bf16 v[68:71], v[144:147], v[184:187], v[68:71]
	v_mfma_f32_16x16x32_bf16 v[64:67], v[152:155], v[184:187], v[64:67]
	v_mfma_f32_16x16x32_bf16 v[116:119], v[148:151], v[164:167], v[116:119]
	v_mfma_f32_16x16x32_bf16 v[112:115], v[156:159], v[164:167], v[112:115]
	v_mfma_f32_16x16x32_bf16 v[100:103], v[148:151], v[172:175], v[100:103]
	v_mfma_f32_16x16x32_bf16 v[96:99], v[156:159], v[172:175], v[96:99]
	v_mfma_f32_16x16x32_bf16 v[84:87], v[148:151], v[180:183], v[84:87]
	v_mfma_f32_16x16x32_bf16 v[80:83], v[156:159], v[180:183], v[80:83]
	v_mfma_f32_16x16x32_bf16 v[68:71], v[148:151], v[188:191], v[68:71]
	v_mfma_f32_16x16x32_bf16 v[64:67], v[156:159], v[188:191], v[64:67]
	s_setprio 0
	s_barrier
	s_add_i32 s42, s77, s35
	s_mov_b32 m0, s42
	ds_read_b128 v[160:163], v231 offset:16384
	ds_read_b128 v[164:167], v231 offset:17408
	ds_read_b128 v[168:171], v231 offset:18432
	ds_read_b128 v[172:175], v231 offset:19456
	ds_read_b128 v[176:179], v231 offset:20480
	ds_read_b128 v[180:183], v231 offset:21504
	ds_read_b128 v[184:187], v231 offset:22528
	ds_read_b128 v[188:191], v231 offset:23552
	global_load_lds_dwordx4 v194, s[48:49]
	s_add_i32 m0, s42, 0x2000
	s_add_u32 s42, s48, 0x40000
	s_addc_u32 s43, s49, 0
	s_add_i32 s84, s78, s35
	global_load_lds_dwordx4 v198, s[48:49]
	s_mov_b32 m0, s84
	s_nop 0
	global_load_lds_dwordx4 v194, s[42:43]
	s_add_i32 m0, s84, 0x2000
	s_nop 0
	global_load_lds_dwordx4 v198, s[42:43]
	s_mov_b32 m0, s23
	s_nop 0
	global_load_lds_dwordx4 v192, s[50:51]
	s_mov_b32 m0, s56
	s_nop 0
	global_load_lds_dwordx4 v196, s[50:51]
	s_waitcnt vmcnt(8)
	s_waitcnt lgkmcnt(0)
	s_barrier
	s_setprio 1
	v_mfma_f32_16x16x32_bf16 v[60:63], v[128:131], v[160:163], v[60:63]
	v_mfma_f32_16x16x32_bf16 v[56:59], v[136:139], v[160:163], v[56:59]
	v_mfma_f32_16x16x32_bf16 v[44:47], v[128:131], v[168:171], v[44:47]
	v_mfma_f32_16x16x32_bf16 v[40:43], v[136:139], v[168:171], v[40:43]
	v_mfma_f32_16x16x32_bf16 v[28:31], v[128:131], v[176:179], v[28:31]
	v_mfma_f32_16x16x32_bf16 v[24:27], v[136:139], v[176:179], v[24:27]
	v_mfma_f32_16x16x32_bf16 v[12:15], v[128:131], v[184:187], v[12:15]
	v_mfma_f32_16x16x32_bf16 v[8:11], v[136:139], v[184:187], v[8:11]
	v_mfma_f32_16x16x32_bf16 v[60:63], v[132:135], v[164:167], v[60:63]
	v_mfma_f32_16x16x32_bf16 v[56:59], v[140:143], v[164:167], v[56:59]
	v_mfma_f32_16x16x32_bf16 v[44:47], v[132:135], v[172:175], v[44:47]
	v_mfma_f32_16x16x32_bf16 v[40:43], v[140:143], v[172:175], v[40:43]
	v_mfma_f32_16x16x32_bf16 v[28:31], v[132:135], v[180:183], v[28:31]
	v_mfma_f32_16x16x32_bf16 v[24:27], v[140:143], v[180:183], v[24:27]
	v_mfma_f32_16x16x32_bf16 v[12:15], v[132:135], v[188:191], v[12:15]
	v_mfma_f32_16x16x32_bf16 v[8:11], v[140:143], v[188:191], v[8:11]
	v_mfma_f32_16x16x32_bf16 v[52:55], v[144:147], v[160:163], v[52:55]
	v_mfma_f32_16x16x32_bf16 v[48:51], v[152:155], v[160:163], v[48:51]
	v_mfma_f32_16x16x32_bf16 v[36:39], v[144:147], v[168:171], v[36:39]
	v_mfma_f32_16x16x32_bf16 v[32:35], v[152:155], v[168:171], v[32:35]
	v_mfma_f32_16x16x32_bf16 v[20:23], v[144:147], v[176:179], v[20:23]
	v_mfma_f32_16x16x32_bf16 v[16:19], v[152:155], v[176:179], v[16:19]
	v_mfma_f32_16x16x32_bf16 v[4:7], v[144:147], v[184:187], v[4:7]
	v_mfma_f32_16x16x32_bf16 v[0:3], v[152:155], v[184:187], v[0:3]
	v_mfma_f32_16x16x32_bf16 v[52:55], v[148:151], v[164:167], v[52:55]
	v_mfma_f32_16x16x32_bf16 v[48:51], v[156:159], v[164:167], v[48:51]
	v_mfma_f32_16x16x32_bf16 v[36:39], v[148:151], v[172:175], v[36:39]
	v_mfma_f32_16x16x32_bf16 v[32:35], v[156:159], v[172:175], v[32:35]
	v_mfma_f32_16x16x32_bf16 v[20:23], v[148:151], v[180:183], v[20:23]
	v_mfma_f32_16x16x32_bf16 v[16:19], v[156:159], v[180:183], v[16:19]
	v_mfma_f32_16x16x32_bf16 v[4:7], v[148:151], v[188:191], v[4:7]
	v_mfma_f32_16x16x32_bf16 v[0:3], v[156:159], v[188:191], v[0:3]
	s_setprio 0
	s_barrier
	s_add_i32 s84, 0, 0x18000
	s_add_i32 s85, 0, 0x1c000
	v_add_u32_e32 v140, s84, v228
	v_add_u32_e32 v156, s85, v228
	ds_read_b128 v[128:131], v140
	ds_read_b128 v[132:135], v140 offset:1024
	ds_read_b128 v[136:139], v140 offset:2048
	ds_read_b128 v[140:143], v140 offset:3072
	ds_read_b128 v[144:147], v156
	ds_read_b128 v[148:151], v156 offset:1024
	ds_read_b128 v[152:155], v156 offset:2048
	ds_read_b128 v[156:159], v156 offset:3072
	s_add_u32 s42, s50, 0x2000
	s_addc_u32 s43, s51, 0
	s_mov_b32 m0, s57
	ds_read_b128 v[160:163], v231 offset:32768
	ds_read_b128 v[164:167], v231 offset:33792
	ds_read_b128 v[168:171], v231 offset:34816
	ds_read_b128 v[172:175], v231 offset:35840
	ds_read_b128 v[176:179], v231 offset:36864
	ds_read_b128 v[180:183], v231 offset:37888
	ds_read_b128 v[184:187], v231 offset:38912
	ds_read_b128 v[188:191], v231 offset:39936
	global_load_lds_dwordx4 v192, s[42:43]
	s_mov_b32 m0, s59
	s_nop 0
	global_load_lds_dwordx4 v196, s[42:43]
	s_waitcnt vmcnt(8)
	s_waitcnt lgkmcnt(0)
	s_barrier
	s_setprio 1
	v_mfma_f32_16x16x32_bf16 v[124:127], v[128:131], v[160:163], v[124:127]
	v_mfma_f32_16x16x32_bf16 v[120:123], v[136:139], v[160:163], v[120:123]
	v_mfma_f32_16x16x32_bf16 v[108:111], v[128:131], v[168:171], v[108:111]
	v_mfma_f32_16x16x32_bf16 v[104:107], v[136:139], v[168:171], v[104:107]
	v_mfma_f32_16x16x32_bf16 v[92:95], v[128:131], v[176:179], v[92:95]
	v_mfma_f32_16x16x32_bf16 v[88:91], v[136:139], v[176:179], v[88:91]
	v_mfma_f32_16x16x32_bf16 v[76:79], v[128:131], v[184:187], v[76:79]
	v_mfma_f32_16x16x32_bf16 v[72:75], v[136:139], v[184:187], v[72:75]
	v_mfma_f32_16x16x32_bf16 v[124:127], v[132:135], v[164:167], v[124:127]
	v_mfma_f32_16x16x32_bf16 v[120:123], v[140:143], v[164:167], v[120:123]
	v_mfma_f32_16x16x32_bf16 v[108:111], v[132:135], v[172:175], v[108:111]
	v_mfma_f32_16x16x32_bf16 v[104:107], v[140:143], v[172:175], v[104:107]
	v_mfma_f32_16x16x32_bf16 v[92:95], v[132:135], v[180:183], v[92:95]
	v_mfma_f32_16x16x32_bf16 v[88:91], v[140:143], v[180:183], v[88:91]
	v_mfma_f32_16x16x32_bf16 v[76:79], v[132:135], v[188:191], v[76:79]
	v_mfma_f32_16x16x32_bf16 v[72:75], v[140:143], v[188:191], v[72:75]
	v_mfma_f32_16x16x32_bf16 v[116:119], v[144:147], v[160:163], v[116:119]
	v_mfma_f32_16x16x32_bf16 v[112:115], v[152:155], v[160:163], v[112:115]
	v_mfma_f32_16x16x32_bf16 v[100:103], v[144:147], v[168:171], v[100:103]
	v_mfma_f32_16x16x32_bf16 v[96:99], v[152:155], v[168:171], v[96:99]
	v_mfma_f32_16x16x32_bf16 v[84:87], v[144:147], v[176:179], v[84:87]
	v_mfma_f32_16x16x32_bf16 v[80:83], v[152:155], v[176:179], v[80:83]
	v_mfma_f32_16x16x32_bf16 v[68:71], v[144:147], v[184:187], v[68:71]
	v_mfma_f32_16x16x32_bf16 v[64:67], v[152:155], v[184:187], v[64:67]
	v_mfma_f32_16x16x32_bf16 v[116:119], v[148:151], v[164:167], v[116:119]
	v_mfma_f32_16x16x32_bf16 v[112:115], v[156:159], v[164:167], v[112:115]
	v_mfma_f32_16x16x32_bf16 v[100:103], v[148:151], v[172:175], v[100:103]
	v_mfma_f32_16x16x32_bf16 v[96:99], v[156:159], v[172:175], v[96:99]
	v_mfma_f32_16x16x32_bf16 v[84:87], v[148:151], v[180:183], v[84:87]
	v_mfma_f32_16x16x32_bf16 v[80:83], v[156:159], v[180:183], v[80:83]
	v_mfma_f32_16x16x32_bf16 v[68:71], v[148:151], v[188:191], v[68:71]
	v_mfma_f32_16x16x32_bf16 v[64:67], v[156:159], v[188:191], v[64:67]
	s_setprio 0
	s_barrier
	s_add_u32 s98, s48, s16
	s_addc_u32 s99, s49, s17
	s_add_i32 s42, s84, s35
	s_mov_b32 m0, s42
	ds_read_b128 v[160:163], v231 offset:49152
	ds_read_b128 v[164:167], v231 offset:50176
	ds_read_b128 v[168:171], v231 offset:51200
	ds_read_b128 v[172:175], v231 offset:52224
	ds_read_b128 v[176:179], v231 offset:53248
	ds_read_b128 v[180:183], v231 offset:54272
	ds_read_b128 v[184:187], v231 offset:55296
	ds_read_b128 v[188:191], v231 offset:56320
	global_load_lds_dwordx4 v194, s[98:99]
	s_add_i32 m0, s42, 0x2000
	s_add_u32 s42, s48, 0x40080
	s_addc_u32 s43, s49, 0
	s_add_i32 s48, s85, s35
	global_load_lds_dwordx4 v198, s[98:99]
	s_mov_b32 m0, s48
	s_nop 0
	global_load_lds_dwordx4 v194, s[42:43]
	s_add_i32 m0, s48, 0x2000
	s_nop 0
	global_load_lds_dwordx4 v198, s[42:43]
	s_mov_b32 m0, s75
	s_nop 0
	global_load_lds_dwordx4 v192, s[46:47]
	s_mov_b32 m0, s76
	s_nop 0
	global_load_lds_dwordx4 v196, s[46:47]
	s_waitcnt vmcnt(8)
	s_waitcnt lgkmcnt(0)
	s_barrier
	s_setprio 1
	v_mfma_f32_16x16x32_bf16 v[60:63], v[128:131], v[160:163], v[60:63]
	v_mfma_f32_16x16x32_bf16 v[56:59], v[136:139], v[160:163], v[56:59]
	v_mfma_f32_16x16x32_bf16 v[44:47], v[128:131], v[168:171], v[44:47]
	v_mfma_f32_16x16x32_bf16 v[40:43], v[136:139], v[168:171], v[40:43]
	v_mfma_f32_16x16x32_bf16 v[28:31], v[128:131], v[176:179], v[28:31]
	v_mfma_f32_16x16x32_bf16 v[24:27], v[136:139], v[176:179], v[24:27]
	v_mfma_f32_16x16x32_bf16 v[12:15], v[128:131], v[184:187], v[12:15]
	v_mfma_f32_16x16x32_bf16 v[8:11], v[136:139], v[184:187], v[8:11]
	v_mfma_f32_16x16x32_bf16 v[60:63], v[132:135], v[164:167], v[60:63]
	v_mfma_f32_16x16x32_bf16 v[56:59], v[140:143], v[164:167], v[56:59]
	v_mfma_f32_16x16x32_bf16 v[44:47], v[132:135], v[172:175], v[44:47]
	v_mfma_f32_16x16x32_bf16 v[40:43], v[140:143], v[172:175], v[40:43]
	v_mfma_f32_16x16x32_bf16 v[28:31], v[132:135], v[180:183], v[28:31]
	v_mfma_f32_16x16x32_bf16 v[24:27], v[140:143], v[180:183], v[24:27]
	v_mfma_f32_16x16x32_bf16 v[12:15], v[132:135], v[188:191], v[12:15]
	v_mfma_f32_16x16x32_bf16 v[8:11], v[140:143], v[188:191], v[8:11]
	v_mfma_f32_16x16x32_bf16 v[52:55], v[144:147], v[160:163], v[52:55]
	v_mfma_f32_16x16x32_bf16 v[48:51], v[152:155], v[160:163], v[48:51]
	v_mfma_f32_16x16x32_bf16 v[36:39], v[144:147], v[168:171], v[36:39]
	v_mfma_f32_16x16x32_bf16 v[32:35], v[152:155], v[168:171], v[32:35]
	v_mfma_f32_16x16x32_bf16 v[20:23], v[144:147], v[176:179], v[20:23]
	v_mfma_f32_16x16x32_bf16 v[16:19], v[152:155], v[176:179], v[16:19]
	v_mfma_f32_16x16x32_bf16 v[4:7], v[144:147], v[184:187], v[4:7]
	v_mfma_f32_16x16x32_bf16 v[0:3], v[152:155], v[184:187], v[0:3]
	v_mfma_f32_16x16x32_bf16 v[52:55], v[148:151], v[164:167], v[52:55]
	v_mfma_f32_16x16x32_bf16 v[48:51], v[156:159], v[164:167], v[48:51]
	v_mfma_f32_16x16x32_bf16 v[36:39], v[148:151], v[172:175], v[36:39]
	v_mfma_f32_16x16x32_bf16 v[32:35], v[156:159], v[172:175], v[32:35]
	v_mfma_f32_16x16x32_bf16 v[20:23], v[148:151], v[180:183], v[20:23]
	v_mfma_f32_16x16x32_bf16 v[16:19], v[156:159], v[180:183], v[16:19]
	v_mfma_f32_16x16x32_bf16 v[4:7], v[148:151], v[188:191], v[4:7]
	v_mfma_f32_16x16x32_bf16 v[0:3], v[156:159], v[188:191], v[0:3]
	s_setprio 0
	s_barrier
	s_add_i32 s83, s83, 2
	s_add_u32 s80, s80, 0x100
	s_addc_u32 s81, s81, 0
	s_cmp_gt_u32 s83, 13
	s_mov_b64 s[42:43], s[44:45]
	s_cbranch_scc0 .LBB0_507
	v_mov_b32_e32 v233, v227
	v_mov_b32_e32 v144, v226
	s_lshl_b32 s8, s22, 8
	s_or_b32 s8, s8, s73
	v_lshlrev_b32_e32 v208, 3, v233
	v_add_u32_e32 v128, s8, v208
	s_lshr_b32 s8, s20, 4
	s_mul_i32 s42, s8, 0x1800
	s_ashr_i32 s43, s42, 31
	s_lshl_b64 s[42:43], s[42:43], 2
	s_add_u32 s42, s69, s42
	v_ashrrev_i32_e32 v129, 31, v128
	v_add_u32_e32 v210, s72, v144
	s_addc_u32 s43, s70, s43
	v_lshlrev_b64 v[212:213], 2, v[128:129]
	v_lshl_add_u32 v216, s20, 8, v210
	v_lshl_add_u64 v[214:215], s[42:43], 0, v[212:213]
	v_ashrrev_i32_e32 v217, 31, v216
	v_add_co_u32_e32 v128, vcc, s65, v214
	v_lshl_add_u64 v[218:219], s[36:37], 0, v[212:213]
	v_lshlrev_b64 v[144:145], 12, v[216:217]
	v_add_u32_e32 v224, 16, v216
	v_lshl_add_u64 v[132:133], v[214:215], 0, s[10:11]
	v_addc_co_u32_e32 v129, vcc, 0, v215, vcc
	v_lshl_add_u64 v[144:145], v[218:219], 0, v[144:145]
	v_ashrrev_i32_e32 v225, 31, v224
	global_load_dwordx4 v[140:143], v[128:129], off nt
	s_nop 0
	global_load_dwordx4 v[128:131], v[132:133], off offset:528 nt
	global_load_dwordx4 v[136:139], v[132:133], off offset:16 nt
	s_nop 0
	global_load_dwordx4 v[132:135], v[132:133], off offset:512 nt
	s_nop 0
	global_load_dwordx4 v[234:237], v[144:145], off offset:16 nt
	global_load_dwordx4 v[238:241], v[144:145], off nt
	global_load_dwordx4 v[242:245], v[144:145], off offset:528 nt
	global_load_dwordx4 v[246:249], v[144:145], off offset:512 nt
	v_lshlrev_b64 v[144:145], 12, v[224:225]
	v_add_u32_e32 v222, 32, v216
	v_lshl_add_u64 v[144:145], v[218:219], 0, v[144:145]
	v_ashrrev_i32_e32 v223, 31, v222
	global_load_dwordx4 v[184:187], v[144:145], off offset:16 nt
	global_load_dwordx4 v[188:191], v[144:145], off nt
	global_load_dwordx4 v[176:179], v[144:145], off offset:528 nt
	global_load_dwordx4 v[180:183], v[144:145], off offset:512 nt
	v_lshlrev_b64 v[144:145], 12, v[222:223]
	v_add_u32_e32 v220, 48, v216
	v_lshl_add_u64 v[144:145], v[218:219], 0, v[144:145]
	v_ashrrev_i32_e32 v221, 31, v220
	global_load_dwordx4 v[168:171], v[144:145], off offset:16 nt
	global_load_dwordx4 v[172:175], v[144:145], off nt
	global_load_dwordx4 v[160:163], v[144:145], off offset:528 nt
	global_load_dwordx4 v[164:167], v[144:145], off offset:512 nt
	v_lshlrev_b64 v[144:145], 12, v[220:221]
	v_lshl_add_u64 v[148:149], v[218:219], 0, v[144:145]
	global_load_dwordx4 v[152:155], v[148:149], off offset:16 nt
	global_load_dwordx4 v[156:159], v[148:149], off nt
	global_load_dwordx4 v[144:147], v[148:149], off offset:528 nt
	s_nop 0
	global_load_dwordx4 v[148:151], v[148:149], off offset:512 nt
	v_and_b32_e32 v211, 64, v232
	v_xor_b32_e32 v209, 16, v232
	v_add_u32_e32 v211, 64, v211
	v_cmp_lt_i32_e32 vcc, v209, v211
	v_xor_b32_e32 v250, 32, v232
	s_lshl_b32 s42, s22, 2
	v_cndmask_b32_e32 v209, v232, v209, vcc
	v_cmp_lt_i32_e32 vcc, v250, v211
	v_lshlrev_b32_e32 v209, 2, v209
	s_ashr_i32 s43, s42, 31
	v_cndmask_b32_e32 v211, v232, v250, vcc
	v_lshlrev_b32_e32 v211, 2, v211
	v_cmp_eq_u32_e32 vcc, 0, v233
	s_waitcnt vmcnt(0)
	v_pk_fma_f32 v[126:127], v[126:127], v[142:143], v[240:241]
	v_pk_fma_f32 v[124:125], v[124:125], v[140:141], v[238:239]
	v_pk_fma_f32 v[120:121], v[120:121], v[136:137], v[234:235]
	v_mul_f32_e32 v233, v125, v125
	v_mul_f32_e32 v234, v127, v127
	v_fmac_f32_e32 v233, v124, v124
	v_fmac_f32_e32 v234, v126, v126
	v_add_f32_e32 v233, v233, v234
	v_mul_f32_e32 v234, v121, v121
	v_pk_fma_f32 v[122:123], v[122:123], v[138:139], v[236:237]
	v_fmac_f32_e32 v234, v120, v120
	v_add_f32_e32 v233, v233, v234
	v_mul_f32_e32 v234, v123, v123
	v_fmac_f32_e32 v234, v122, v122
	v_pk_fma_f32 v[118:119], v[118:119], v[134:135], v[248:249]
	v_pk_fma_f32 v[116:117], v[116:117], v[132:133], v[246:247]
	v_add_f32_e32 v233, v234, v233
	v_mul_f32_e32 v234, v117, v117
	v_mul_f32_e32 v235, v119, v119
	v_pk_fma_f32 v[112:113], v[112:113], v[128:129], v[242:243]
	v_fmac_f32_e32 v234, v116, v116
	v_fmac_f32_e32 v235, v118, v118
	v_add_f32_e32 v234, v234, v235
	v_mul_f32_e32 v235, v113, v113
	v_pk_fma_f32 v[114:115], v[114:115], v[130:131], v[244:245]
	v_fmac_f32_e32 v235, v112, v112
	v_add_f32_e32 v234, v234, v235
	v_mul_f32_e32 v235, v115, v115
	v_fmac_f32_e32 v235, v114, v114
	v_add_f32_e32 v234, v235, v234
	v_add_f32_e32 v233, v233, v234
	ds_bpermute_b32 v234, v209, v233
	s_waitcnt lgkmcnt(0)
	v_add_f32_e32 v233, v233, v234
	ds_bpermute_b32 v234, v211, v233
	s_and_saveexec_b64 s[44:45], vcc
	s_cbranch_execz .LBB0_510
	v_lshlrev_b64 v[236:237], 6, v[216:217]
	v_lshl_add_u64 v[236:237], s[12:13], 0, v[236:237]
	v_lshl_add_u64 v[236:237], s[42:43], 2, v[236:237]
	s_lshl_b32 s8, s71, 2
	v_lshl_add_u64 v[236:237], v[236:237], 0, s[8:9]
	s_waitcnt lgkmcnt(0)
	v_add_f32_e32 v217, v233, v234
	global_store_dword v[236:237], v217, off

.LBB0_568:
	ds_read_b128 v[128:131], v167
	ds_read_b128 v[132:135], v167 offset:1024
	ds_read_b128 v[136:139], v167 offset:2048
	ds_read_b128 v[140:143], v167 offset:3072
	ds_read_b128 v[160:163], v168
	ds_read_b128 v[170:173], v168 offset:1024
	ds_read_b128 v[174:177], v168 offset:2048
	ds_read_b128 v[178:181], v168 offset:3072
	s_add_u32 s36, s28, 0x10000
	s_addc_u32 s37, s29, 0
	s_cmp_eq_u32 s76, 12
	s_cselect_b32 s42, s27, s36
	s_cselect_b32 s43, s19, s37
	s_cselect_b32 s40, s73, s74
	s_cselect_b32 s41, s17, s75
	s_add_u32 s38, s42, 0x8000
	s_addc_u32 s39, s43, 0
	s_add_i32 m0, s44, 0xc000
	ds_read_b128 v[182:185], v169
	ds_read_b128 v[186:189], v169 offset:1024
	ds_read_b128 v[190:193], v169 offset:2048
	ds_read_b128 v[194:197], v169 offset:3072
	ds_read_b128 v[198:201], v169 offset:4096
	ds_read_b128 v[202:205], v169 offset:5120
	ds_read_b128 v[206:209], v169 offset:6144
	ds_read_b128 v[210:213], v169 offset:7168
	global_load_lds_dwordx4 v152, s[28:29]
	s_add_i32 m0, s44, 0xe000
	s_nop 0
	global_load_lds_dwordx4 v154, s[28:29]
	s_waitcnt vmcnt(8)
	s_waitcnt lgkmcnt(0)
	s_barrier
	s_setprio 1
	v_mfma_f32_16x16x32_bf16 v[124:127], v[128:131], v[182:185], v[124:127]
	v_mfma_f32_16x16x32_bf16 v[120:123], v[136:139], v[182:185], v[120:123]
	v_mfma_f32_16x16x32_bf16 v[116:119], v[128:131], v[190:193], v[116:119]
	v_mfma_f32_16x16x32_bf16 v[112:115], v[136:139], v[190:193], v[112:115]
	v_mfma_f32_16x16x32_bf16 v[92:95], v[128:131], v[198:201], v[92:95]
	v_mfma_f32_16x16x32_bf16 v[88:91], v[136:139], v[198:201], v[88:91]
	v_mfma_f32_16x16x32_bf16 v[76:79], v[128:131], v[206:209], v[76:79]
	v_mfma_f32_16x16x32_bf16 v[72:75], v[136:139], v[206:209], v[72:75]
	v_mfma_f32_16x16x32_bf16 v[124:127], v[132:135], v[186:189], v[124:127]
	v_mfma_f32_16x16x32_bf16 v[120:123], v[140:143], v[186:189], v[120:123]
	v_mfma_f32_16x16x32_bf16 v[116:119], v[132:135], v[194:197], v[116:119]
	v_mfma_f32_16x16x32_bf16 v[112:115], v[140:143], v[194:197], v[112:115]
	v_mfma_f32_16x16x32_bf16 v[92:95], v[132:135], v[202:205], v[92:95]
	v_mfma_f32_16x16x32_bf16 v[88:91], v[140:143], v[202:205], v[88:91]
	v_mfma_f32_16x16x32_bf16 v[76:79], v[132:135], v[210:213], v[76:79]
	v_mfma_f32_16x16x32_bf16 v[72:75], v[140:143], v[210:213], v[72:75]
	v_mfma_f32_16x16x32_bf16 v[108:111], v[160:163], v[182:185], v[108:111]
	v_mfma_f32_16x16x32_bf16 v[104:107], v[174:177], v[182:185], v[104:107]
	v_mfma_f32_16x16x32_bf16 v[100:103], v[160:163], v[190:193], v[100:103]
	v_mfma_f32_16x16x32_bf16 v[96:99], v[174:177], v[190:193], v[96:99]
	v_mfma_f32_16x16x32_bf16 v[84:87], v[160:163], v[198:201], v[84:87]
	v_mfma_f32_16x16x32_bf16 v[80:83], v[174:177], v[198:201], v[80:83]
	v_mfma_f32_16x16x32_bf16 v[68:71], v[160:163], v[206:209], v[68:71]
	v_mfma_f32_16x16x32_bf16 v[64:67], v[174:177], v[206:209], v[64:67]
	v_mfma_f32_16x16x32_bf16 v[108:111], v[170:173], v[186:189], v[108:111]
	v_mfma_f32_16x16x32_bf16 v[104:107], v[178:181], v[186:189], v[104:107]
	v_mfma_f32_16x16x32_bf16 v[100:103], v[170:173], v[194:197], v[100:103]
	v_mfma_f32_16x16x32_bf16 v[96:99], v[178:181], v[194:197], v[96:99]
	v_mfma_f32_16x16x32_bf16 v[84:87], v[170:173], v[202:205], v[84:87]
	v_mfma_f32_16x16x32_bf16 v[80:83], v[178:181], v[202:205], v[80:83]
	v_mfma_f32_16x16x32_bf16 v[68:71], v[170:173], v[210:213], v[68:71]
	v_mfma_f32_16x16x32_bf16 v[64:67], v[178:181], v[210:213], v[64:67]
	s_setprio 0
	s_barrier
	s_add_i32 s28, s70, s35
	s_mov_b32 m0, s28
	ds_read_b128 v[182:185], v169 offset:16384
	ds_read_b128 v[186:189], v169 offset:17408
	ds_read_b128 v[190:193], v169 offset:18432
	ds_read_b128 v[194:197], v169 offset:19456
	ds_read_b128 v[198:201], v169 offset:20480
	ds_read_b128 v[202:205], v169 offset:21504
	ds_read_b128 v[206:209], v169 offset:22528
	ds_read_b128 v[210:213], v169 offset:23552
	global_load_lds_dwordx4 v148, s[40:41]
	s_add_i32 m0, s28, 0x2000
	s_add_u32 s28, s40, 0x40000
	s_addc_u32 s29, s41, 0
	s_add_i32 s77, s71, s35
	global_load_lds_dwordx4 v144, s[40:41]
	s_mov_b32 m0, s77
	s_nop 0
	global_load_lds_dwordx4 v148, s[28:29]
	s_add_i32 m0, s77, 0x2000
	s_nop 0
	global_load_lds_dwordx4 v144, s[28:29]
	s_mov_b32 m0, s44
	s_nop 0
	global_load_lds_dwordx4 v150, s[42:43]
	s_mov_b32 m0, s45
	s_nop 0
	global_load_lds_dwordx4 v146, s[42:43]
	s_waitcnt vmcnt(8)
	s_waitcnt lgkmcnt(0)
	s_barrier
	s_setprio 1
	v_mfma_f32_16x16x32_bf16 v[60:63], v[128:131], v[182:185], v[60:63]
	v_mfma_f32_16x16x32_bf16 v[56:59], v[136:139], v[182:185], v[56:59]
	v_mfma_f32_16x16x32_bf16 v[44:47], v[128:131], v[190:193], v[44:47]
	v_mfma_f32_16x16x32_bf16 v[40:43], v[136:139], v[190:193], v[40:43]
	v_mfma_f32_16x16x32_bf16 v[28:31], v[128:131], v[198:201], v[28:31]
	v_mfma_f32_16x16x32_bf16 v[24:27], v[136:139], v[198:201], v[24:27]
	v_mfma_f32_16x16x32_bf16 v[12:15], v[128:131], v[206:209], v[12:15]
	v_mfma_f32_16x16x32_bf16 v[8:11], v[136:139], v[206:209], v[8:11]
	v_mfma_f32_16x16x32_bf16 v[60:63], v[132:135], v[186:189], v[60:63]
	v_mfma_f32_16x16x32_bf16 v[56:59], v[140:143], v[186:189], v[56:59]
	v_mfma_f32_16x16x32_bf16 v[44:47], v[132:135], v[194:197], v[44:47]
	v_mfma_f32_16x16x32_bf16 v[40:43], v[140:143], v[194:197], v[40:43]
	v_mfma_f32_16x16x32_bf16 v[28:31], v[132:135], v[202:205], v[28:31]
	v_mfma_f32_16x16x32_bf16 v[24:27], v[140:143], v[202:205], v[24:27]
	v_mfma_f32_16x16x32_bf16 v[12:15], v[132:135], v[210:213], v[12:15]
	v_mfma_f32_16x16x32_bf16 v[8:11], v[140:143], v[210:213], v[8:11]
	v_mfma_f32_16x16x32_bf16 v[52:55], v[160:163], v[182:185], v[52:55]
	v_mfma_f32_16x16x32_bf16 v[48:51], v[174:177], v[182:185], v[48:51]
	v_mfma_f32_16x16x32_bf16 v[36:39], v[160:163], v[190:193], v[36:39]
	v_mfma_f32_16x16x32_bf16 v[32:35], v[174:177], v[190:193], v[32:35]
	v_mfma_f32_16x16x32_bf16 v[20:23], v[160:163], v[198:201], v[20:23]
	v_mfma_f32_16x16x32_bf16 v[16:19], v[174:177], v[198:201], v[16:19]
	v_mfma_f32_16x16x32_bf16 v[4:7], v[160:163], v[206:209], v[4:7]
	v_mfma_f32_16x16x32_bf16 v[0:3], v[174:177], v[206:209], v[0:3]
	v_mfma_f32_16x16x32_bf16 v[52:55], v[170:173], v[186:189], v[52:55]
	v_mfma_f32_16x16x32_bf16 v[48:51], v[178:181], v[186:189], v[48:51]
	v_mfma_f32_16x16x32_bf16 v[36:39], v[170:173], v[194:197], v[36:39]
	v_mfma_f32_16x16x32_bf16 v[32:35], v[178:181], v[194:197], v[32:35]
	v_mfma_f32_16x16x32_bf16 v[20:23], v[170:173], v[202:205], v[20:23]
	v_mfma_f32_16x16x32_bf16 v[16:19], v[178:181], v[202:205], v[16:19]
	v_mfma_f32_16x16x32_bf16 v[4:7], v[170:173], v[210:213], v[4:7]
	v_mfma_f32_16x16x32_bf16 v[0:3], v[178:181], v[210:213], v[0:3]
	s_setprio 0
	s_barrier
	s_add_i32 s77, 0, 0x18000
	s_add_i32 s78, 0, 0x1c000
	v_add_u32_e32 v140, s77, v166
	v_add_u32_e32 v178, s78, v166
	ds_read_b128 v[128:131], v140
	ds_read_b128 v[132:135], v140 offset:1024
	ds_read_b128 v[136:139], v140 offset:2048
	ds_read_b128 v[140:143], v140 offset:3072
	ds_read_b128 v[160:163], v178
	ds_read_b128 v[170:173], v178 offset:1024
	ds_read_b128 v[174:177], v178 offset:2048
	ds_read_b128 v[178:181], v178 offset:3072
	s_add_u32 s28, s42, 0x2000
	s_addc_u32 s29, s43, 0
	s_mov_b32 m0, s46
	ds_read_b128 v[182:185], v169 offset:32768
	ds_read_b128 v[186:189], v169 offset:33792
	ds_read_b128 v[190:193], v169 offset:34816
	ds_read_b128 v[194:197], v169 offset:35840
	ds_read_b128 v[198:201], v169 offset:36864
	ds_read_b128 v[202:205], v169 offset:37888
	ds_read_b128 v[206:209], v169 offset:38912
	ds_read_b128 v[210:213], v169 offset:39936
	global_load_lds_dwordx4 v150, s[28:29]
	s_mov_b32 m0, s47
	s_nop 0
	global_load_lds_dwordx4 v146, s[28:29]
	s_waitcnt vmcnt(8)
	s_waitcnt lgkmcnt(0)
	s_barrier
	s_setprio 1
	v_mfma_f32_16x16x32_bf16 v[124:127], v[128:131], v[182:185], v[124:127]
	v_mfma_f32_16x16x32_bf16 v[120:123], v[136:139], v[182:185], v[120:123]
	v_mfma_f32_16x16x32_bf16 v[116:119], v[128:131], v[190:193], v[116:119]
	v_mfma_f32_16x16x32_bf16 v[112:115], v[136:139], v[190:193], v[112:115]
	v_mfma_f32_16x16x32_bf16 v[92:95], v[128:131], v[198:201], v[92:95]
	v_mfma_f32_16x16x32_bf16 v[88:91], v[136:139], v[198:201], v[88:91]
	v_mfma_f32_16x16x32_bf16 v[76:79], v[128:131], v[206:209], v[76:79]
	v_mfma_f32_16x16x32_bf16 v[72:75], v[136:139], v[206:209], v[72:75]
	v_mfma_f32_16x16x32_bf16 v[124:127], v[132:135], v[186:189], v[124:127]
	v_mfma_f32_16x16x32_bf16 v[120:123], v[140:143], v[186:189], v[120:123]
	v_mfma_f32_16x16x32_bf16 v[116:119], v[132:135], v[194:197], v[116:119]
	v_mfma_f32_16x16x32_bf16 v[112:115], v[140:143], v[194:197], v[112:115]
	v_mfma_f32_16x16x32_bf16 v[92:95], v[132:135], v[202:205], v[92:95]
	v_mfma_f32_16x16x32_bf16 v[88:91], v[140:143], v[202:205], v[88:91]
	v_mfma_f32_16x16x32_bf16 v[76:79], v[132:135], v[210:213], v[76:79]
	v_mfma_f32_16x16x32_bf16 v[72:75], v[140:143], v[210:213], v[72:75]
	v_mfma_f32_16x16x32_bf16 v[108:111], v[160:163], v[182:185], v[108:111]
	v_mfma_f32_16x16x32_bf16 v[104:107], v[174:177], v[182:185], v[104:107]
	v_mfma_f32_16x16x32_bf16 v[100:103], v[160:163], v[190:193], v[100:103]
	v_mfma_f32_16x16x32_bf16 v[96:99], v[174:177], v[190:193], v[96:99]
	v_mfma_f32_16x16x32_bf16 v[84:87], v[160:163], v[198:201], v[84:87]
	v_mfma_f32_16x16x32_bf16 v[80:83], v[174:177], v[198:201], v[80:83]
	v_mfma_f32_16x16x32_bf16 v[68:71], v[160:163], v[206:209], v[68:71]
	v_mfma_f32_16x16x32_bf16 v[64:67], v[174:177], v[206:209], v[64:67]
	v_mfma_f32_16x16x32_bf16 v[108:111], v[170:173], v[186:189], v[108:111]
	v_mfma_f32_16x16x32_bf16 v[104:107], v[178:181], v[186:189], v[104:107]
	v_mfma_f32_16x16x32_bf16 v[100:103], v[170:173], v[194:197], v[100:103]
	v_mfma_f32_16x16x32_bf16 v[96:99], v[178:181], v[194:197], v[96:99]
	v_mfma_f32_16x16x32_bf16 v[84:87], v[170:173], v[202:205], v[84:87]
	v_mfma_f32_16x16x32_bf16 v[80:83], v[178:181], v[202:205], v[80:83]
	v_mfma_f32_16x16x32_bf16 v[68:71], v[170:173], v[210:213], v[68:71]
	v_mfma_f32_16x16x32_bf16 v[64:67], v[178:181], v[210:213], v[64:67]
	s_setprio 0
	s_barrier
	s_add_u32 s98, s40, s12
	s_addc_u32 s99, s41, s13
	s_add_i32 s28, s77, s35
	s_mov_b32 m0, s28
	ds_read_b128 v[182:185], v169 offset:49152
	ds_read_b128 v[186:189], v169 offset:50176
	ds_read_b128 v[190:193], v169 offset:51200
	ds_read_b128 v[194:197], v169 offset:52224
	ds_read_b128 v[198:201], v169 offset:53248
	ds_read_b128 v[202:205], v169 offset:54272
	ds_read_b128 v[206:209], v169 offset:55296
	ds_read_b128 v[210:213], v169 offset:56320
	global_load_lds_dwordx4 v148, s[98:99]
	s_add_i32 m0, s28, 0x2000
	s_add_u32 s28, s40, 0x40080
	s_addc_u32 s29, s41, 0
	s_add_i32 s40, s78, s35
	global_load_lds_dwordx4 v144, s[98:99]
	s_mov_b32 m0, s40
	s_nop 0
	global_load_lds_dwordx4 v148, s[28:29]
	s_add_i32 m0, s40, 0x2000
	s_nop 0
	global_load_lds_dwordx4 v144, s[28:29]
	s_mov_b32 m0, s68
	s_nop 0
	global_load_lds_dwordx4 v150, s[38:39]
	s_mov_b32 m0, s69
	s_nop 0
	global_load_lds_dwordx4 v146, s[38:39]
	s_waitcnt vmcnt(8)
	s_waitcnt lgkmcnt(0)
	s_barrier
	s_setprio 1
	v_mfma_f32_16x16x32_bf16 v[60:63], v[128:131], v[182:185], v[60:63]
	v_mfma_f32_16x16x32_bf16 v[56:59], v[136:139], v[182:185], v[56:59]
	v_mfma_f32_16x16x32_bf16 v[44:47], v[128:131], v[190:193], v[44:47]
	v_mfma_f32_16x16x32_bf16 v[40:43], v[136:139], v[190:193], v[40:43]
	v_mfma_f32_16x16x32_bf16 v[28:31], v[128:131], v[198:201], v[28:31]
	v_mfma_f32_16x16x32_bf16 v[24:27], v[136:139], v[198:201], v[24:27]
	v_mfma_f32_16x16x32_bf16 v[12:15], v[128:131], v[206:209], v[12:15]
	v_mfma_f32_16x16x32_bf16 v[8:11], v[136:139], v[206:209], v[8:11]
	v_mfma_f32_16x16x32_bf16 v[60:63], v[132:135], v[186:189], v[60:63]
	v_mfma_f32_16x16x32_bf16 v[56:59], v[140:143], v[186:189], v[56:59]
	v_mfma_f32_16x16x32_bf16 v[44:47], v[132:135], v[194:197], v[44:47]
	v_mfma_f32_16x16x32_bf16 v[40:43], v[140:143], v[194:197], v[40:43]
	v_mfma_f32_16x16x32_bf16 v[28:31], v[132:135], v[202:205], v[28:31]
	v_mfma_f32_16x16x32_bf16 v[24:27], v[140:143], v[202:205], v[24:27]
	v_mfma_f32_16x16x32_bf16 v[12:15], v[132:135], v[210:213], v[12:15]
	v_mfma_f32_16x16x32_bf16 v[8:11], v[140:143], v[210:213], v[8:11]
	v_mfma_f32_16x16x32_bf16 v[52:55], v[160:163], v[182:185], v[52:55]
	v_mfma_f32_16x16x32_bf16 v[48:51], v[174:177], v[182:185], v[48:51]
	v_mfma_f32_16x16x32_bf16 v[36:39], v[160:163], v[190:193], v[36:39]
	v_mfma_f32_16x16x32_bf16 v[32:35], v[174:177], v[190:193], v[32:35]
	v_mfma_f32_16x16x32_bf16 v[20:23], v[160:163], v[198:201], v[20:23]
	v_mfma_f32_16x16x32_bf16 v[16:19], v[174:177], v[198:201], v[16:19]
	v_mfma_f32_16x16x32_bf16 v[4:7], v[160:163], v[206:209], v[4:7]
	v_mfma_f32_16x16x32_bf16 v[0:3], v[174:177], v[206:209], v[0:3]
	v_mfma_f32_16x16x32_bf16 v[52:55], v[170:173], v[186:189], v[52:55]
	v_mfma_f32_16x16x32_bf16 v[48:51], v[178:181], v[186:189], v[48:51]
	v_mfma_f32_16x16x32_bf16 v[36:39], v[170:173], v[194:197], v[36:39]
	v_mfma_f32_16x16x32_bf16 v[32:35], v[178:181], v[194:197], v[32:35]
	v_mfma_f32_16x16x32_bf16 v[20:23], v[170:173], v[202:205], v[20:23]
	v_mfma_f32_16x16x32_bf16 v[16:19], v[178:181], v[202:205], v[16:19]
	v_mfma_f32_16x16x32_bf16 v[4:7], v[170:173], v[210:213], v[4:7]
	v_mfma_f32_16x16x32_bf16 v[0:3], v[178:181], v[210:213], v[0:3]
	s_setprio 0
	s_barrier
	s_add_i32 s76, s76, 2
	s_add_u32 s74, s74, 0x100
	s_addc_u32 s75, s75, 0
	s_cmp_gt_u32 s76, 13
	s_mov_b64 s[28:29], s[36:37]
	s_cbranch_scc0 .LBB0_568
	s_and_b64 vcc, exec, s[10:11]
	s_cbranch_vccz .LBB0_571

.LBB0_615:
	v_add_u32_e32 v151, s51, v149
	ds_read_b128 v[152:155], v151
	ds_read_b128 v[156:159], v151 offset:1024
	ds_read_b128 v[160:163], v151 offset:2048
	ds_read_b128 v[164:167], v151 offset:3072
	v_add_u32_e32 v151, s56, v149
	ds_read_b128 v[168:171], v151
	ds_read_b128 v[172:175], v151 offset:1024
	ds_read_b128 v[176:179], v151 offset:2048
	ds_read_b128 v[180:183], v151 offset:3072
	s_add_u32 s38, s12, s36
	s_addc_u32 s39, s13, s37
	s_cmp_eq_u32 s63, 60
	s_cselect_b32 s42, s59, s38
	s_cselect_b32 s43, s23, s39
	s_cselect_b32 s40, s60, s61
	s_cselect_b32 s41, s21, s62
	s_add_u32 s38, s42, 0x8000
	s_addc_u32 s39, s43, 0
	s_add_i32 m0, s44, 0xc000
	ds_read_b128 v[184:187], v150
	ds_read_b128 v[188:191], v150 offset:1024
	ds_read_b128 v[192:195], v150 offset:2048
	ds_read_b128 v[196:199], v150 offset:3072
	ds_read_b128 v[200:203], v150 offset:4096
	ds_read_b128 v[204:207], v150 offset:5120
	ds_read_b128 v[208:211], v150 offset:6144
	ds_read_b128 v[212:215], v150 offset:7168
	global_load_lds_dwordx4 v146, s[12:13]
	s_add_i32 m0, s44, 0xe000
	s_nop 0
	global_load_lds_dwordx4 v144, s[12:13]
	s_waitcnt vmcnt(8)
	s_waitcnt lgkmcnt(0)
	s_barrier
	s_setprio 1
	v_mfma_f32_16x16x32_bf16 v[124:127], v[152:155], v[184:187], v[124:127]
	v_mfma_f32_16x16x32_bf16 v[120:123], v[160:163], v[184:187], v[120:123]
	v_mfma_f32_16x16x32_bf16 v[108:111], v[152:155], v[192:195], v[108:111]
	v_mfma_f32_16x16x32_bf16 v[104:107], v[160:163], v[192:195], v[104:107]
	v_mfma_f32_16x16x32_bf16 v[92:95], v[152:155], v[200:203], v[92:95]
	v_mfma_f32_16x16x32_bf16 v[88:91], v[160:163], v[200:203], v[88:91]
	v_mfma_f32_16x16x32_bf16 v[76:79], v[152:155], v[208:211], v[76:79]
	v_mfma_f32_16x16x32_bf16 v[72:75], v[160:163], v[208:211], v[72:75]
	v_mfma_f32_16x16x32_bf16 v[124:127], v[156:159], v[188:191], v[124:127]
	v_mfma_f32_16x16x32_bf16 v[120:123], v[164:167], v[188:191], v[120:123]
	v_mfma_f32_16x16x32_bf16 v[108:111], v[156:159], v[196:199], v[108:111]
	v_mfma_f32_16x16x32_bf16 v[104:107], v[164:167], v[196:199], v[104:107]
	v_mfma_f32_16x16x32_bf16 v[92:95], v[156:159], v[204:207], v[92:95]
	v_mfma_f32_16x16x32_bf16 v[88:91], v[164:167], v[204:207], v[88:91]
	v_mfma_f32_16x16x32_bf16 v[76:79], v[156:159], v[212:215], v[76:79]
	v_mfma_f32_16x16x32_bf16 v[72:75], v[164:167], v[212:215], v[72:75]
	v_mfma_f32_16x16x32_bf16 v[116:119], v[168:171], v[184:187], v[116:119]
	v_mfma_f32_16x16x32_bf16 v[112:115], v[176:179], v[184:187], v[112:115]
	v_mfma_f32_16x16x32_bf16 v[100:103], v[168:171], v[192:195], v[100:103]
	v_mfma_f32_16x16x32_bf16 v[96:99], v[176:179], v[192:195], v[96:99]
	v_mfma_f32_16x16x32_bf16 v[84:87], v[168:171], v[200:203], v[84:87]
	v_mfma_f32_16x16x32_bf16 v[80:83], v[176:179], v[200:203], v[80:83]
	v_mfma_f32_16x16x32_bf16 v[68:71], v[168:171], v[208:211], v[68:71]
	v_mfma_f32_16x16x32_bf16 v[64:67], v[176:179], v[208:211], v[64:67]
	v_mfma_f32_16x16x32_bf16 v[116:119], v[172:175], v[188:191], v[116:119]
	v_mfma_f32_16x16x32_bf16 v[112:115], v[180:183], v[188:191], v[112:115]
	v_mfma_f32_16x16x32_bf16 v[100:103], v[172:175], v[196:199], v[100:103]
	v_mfma_f32_16x16x32_bf16 v[96:99], v[180:183], v[196:199], v[96:99]
	v_mfma_f32_16x16x32_bf16 v[84:87], v[172:175], v[204:207], v[84:87]
	v_mfma_f32_16x16x32_bf16 v[80:83], v[180:183], v[204:207], v[80:83]
	v_mfma_f32_16x16x32_bf16 v[68:71], v[172:175], v[212:215], v[68:71]
	v_mfma_f32_16x16x32_bf16 v[64:67], v[180:183], v[212:215], v[64:67]
	s_setprio 0
	s_barrier
	s_add_i32 s64, s51, s35
	s_mov_b32 m0, s64
	ds_read_b128 v[184:187], v150 offset:16384
	ds_read_b128 v[188:191], v150 offset:17408
	ds_read_b128 v[192:195], v150 offset:18432
	ds_read_b128 v[196:199], v150 offset:19456
	ds_read_b128 v[200:203], v150 offset:20480
	ds_read_b128 v[204:207], v150 offset:21504
	ds_read_b128 v[208:211], v150 offset:22528
	ds_read_b128 v[212:215], v150 offset:23552
	global_load_lds_dwordx4 v130, s[40:41]
	s_add_i32 m0, s64, 0x2000
	s_add_u32 s64, s40, 0x100000
	v_lshl_add_u64 v[218:219], s[40:41], 0, v[134:135]
	s_addc_u32 s65, s41, 0
	s_add_i32 s66, s56, s35
	global_load_lds_dwordx4 v[218:219], off
	s_mov_b32 m0, s66
	s_nop 0
	global_load_lds_dwordx4 v130, s[64:65]
	s_add_i32 m0, s66, 0x2000
	s_nop 0
	global_load_lds_dwordx4 v134, s[64:65]
	s_mov_b32 m0, s44
	s_nop 0
	global_load_lds_dwordx4 v128, s[42:43]
	s_mov_b32 m0, s45
	s_nop 0
	global_load_lds_dwordx4 v132, s[42:43]
	s_waitcnt vmcnt(8)
	s_waitcnt lgkmcnt(0)
	s_barrier
	s_setprio 1
	v_mfma_f32_16x16x32_bf16 v[60:63], v[152:155], v[184:187], v[60:63]
	v_mfma_f32_16x16x32_bf16 v[56:59], v[160:163], v[184:187], v[56:59]
	v_mfma_f32_16x16x32_bf16 v[44:47], v[152:155], v[192:195], v[44:47]
	v_mfma_f32_16x16x32_bf16 v[40:43], v[160:163], v[192:195], v[40:43]
	v_mfma_f32_16x16x32_bf16 v[28:31], v[152:155], v[200:203], v[28:31]
	v_mfma_f32_16x16x32_bf16 v[24:27], v[160:163], v[200:203], v[24:27]
	v_mfma_f32_16x16x32_bf16 v[12:15], v[152:155], v[208:211], v[12:15]
	v_mfma_f32_16x16x32_bf16 v[8:11], v[160:163], v[208:211], v[8:11]
	v_mfma_f32_16x16x32_bf16 v[60:63], v[156:159], v[188:191], v[60:63]
	v_mfma_f32_16x16x32_bf16 v[56:59], v[164:167], v[188:191], v[56:59]
	v_mfma_f32_16x16x32_bf16 v[44:47], v[156:159], v[196:199], v[44:47]
	v_mfma_f32_16x16x32_bf16 v[40:43], v[164:167], v[196:199], v[40:43]
	v_mfma_f32_16x16x32_bf16 v[28:31], v[156:159], v[204:207], v[28:31]
	v_mfma_f32_16x16x32_bf16 v[24:27], v[164:167], v[204:207], v[24:27]
	v_mfma_f32_16x16x32_bf16 v[12:15], v[156:159], v[212:215], v[12:15]
	v_mfma_f32_16x16x32_bf16 v[8:11], v[164:167], v[212:215], v[8:11]
	v_mfma_f32_16x16x32_bf16 v[52:55], v[168:171], v[184:187], v[52:55]
	v_mfma_f32_16x16x32_bf16 v[48:51], v[176:179], v[184:187], v[48:51]
	v_mfma_f32_16x16x32_bf16 v[36:39], v[168:171], v[192:195], v[36:39]
	v_mfma_f32_16x16x32_bf16 v[32:35], v[176:179], v[192:195], v[32:35]
	v_mfma_f32_16x16x32_bf16 v[20:23], v[168:171], v[200:203], v[20:23]
	v_mfma_f32_16x16x32_bf16 v[16:19], v[176:179], v[200:203], v[16:19]
	v_mfma_f32_16x16x32_bf16 v[4:7], v[168:171], v[208:211], v[4:7]
	v_mfma_f32_16x16x32_bf16 v[0:3], v[176:179], v[208:211], v[0:3]
	v_mfma_f32_16x16x32_bf16 v[52:55], v[172:175], v[188:191], v[52:55]
	v_mfma_f32_16x16x32_bf16 v[48:51], v[180:183], v[188:191], v[48:51]
	v_mfma_f32_16x16x32_bf16 v[36:39], v[172:175], v[196:199], v[36:39]
	v_mfma_f32_16x16x32_bf16 v[32:35], v[180:183], v[196:199], v[32:35]
	v_mfma_f32_16x16x32_bf16 v[20:23], v[172:175], v[204:207], v[20:23]
	v_mfma_f32_16x16x32_bf16 v[16:19], v[180:183], v[204:207], v[16:19]
	v_mfma_f32_16x16x32_bf16 v[4:7], v[172:175], v[212:215], v[4:7]
	v_mfma_f32_16x16x32_bf16 v[0:3], v[180:183], v[212:215], v[0:3]
	s_setprio 0
	s_barrier
	s_add_i32 s64, 0, 0x18000
	v_add_u32_e32 v151, s64, v149
	s_add_i32 s65, 0, 0x1c000
	ds_read_b128 v[152:155], v151
	ds_read_b128 v[156:159], v151 offset:1024
	ds_read_b128 v[160:163], v151 offset:2048
	ds_read_b128 v[164:167], v151 offset:3072
	v_add_u32_e32 v151, s65, v149
	ds_read_b128 v[168:171], v151
	ds_read_b128 v[172:175], v151 offset:1024
	ds_read_b128 v[176:179], v151 offset:2048
	ds_read_b128 v[180:183], v151 offset:3072
	s_add_u32 s42, s42, 0x2000
	s_addc_u32 s43, s43, 0
	s_mov_b32 m0, s46
	ds_read_b128 v[184:187], v150 offset:32768
	ds_read_b128 v[188:191], v150 offset:33792
	ds_read_b128 v[192:195], v150 offset:34816
	ds_read_b128 v[196:199], v150 offset:35840
	ds_read_b128 v[200:203], v150 offset:36864
	ds_read_b128 v[204:207], v150 offset:37888
	ds_read_b128 v[208:211], v150 offset:38912
	ds_read_b128 v[212:215], v150 offset:39936
	global_load_lds_dwordx4 v128, s[42:43]
	s_mov_b32 m0, s47
	s_nop 0
	global_load_lds_dwordx4 v132, s[42:43]
	s_waitcnt vmcnt(8)
	s_waitcnt lgkmcnt(0)
	s_barrier
	s_setprio 1
	v_mfma_f32_16x16x32_bf16 v[124:127], v[152:155], v[184:187], v[124:127]
	v_mfma_f32_16x16x32_bf16 v[120:123], v[160:163], v[184:187], v[120:123]
	v_mfma_f32_16x16x32_bf16 v[108:111], v[152:155], v[192:195], v[108:111]
	v_mfma_f32_16x16x32_bf16 v[104:107], v[160:163], v[192:195], v[104:107]
	v_mfma_f32_16x16x32_bf16 v[92:95], v[152:155], v[200:203], v[92:95]
	v_mfma_f32_16x16x32_bf16 v[88:91], v[160:163], v[200:203], v[88:91]
	v_mfma_f32_16x16x32_bf16 v[76:79], v[152:155], v[208:211], v[76:79]
	v_mfma_f32_16x16x32_bf16 v[72:75], v[160:163], v[208:211], v[72:75]
	v_mfma_f32_16x16x32_bf16 v[124:127], v[156:159], v[188:191], v[124:127]
	v_mfma_f32_16x16x32_bf16 v[120:123], v[164:167], v[188:191], v[120:123]
	v_mfma_f32_16x16x32_bf16 v[108:111], v[156:159], v[196:199], v[108:111]
	v_mfma_f32_16x16x32_bf16 v[104:107], v[164:167], v[196:199], v[104:107]
	v_mfma_f32_16x16x32_bf16 v[92:95], v[156:159], v[204:207], v[92:95]
	v_mfma_f32_16x16x32_bf16 v[88:91], v[164:167], v[204:207], v[88:91]
	v_mfma_f32_16x16x32_bf16 v[76:79], v[156:159], v[212:215], v[76:79]
	v_mfma_f32_16x16x32_bf16 v[72:75], v[164:167], v[212:215], v[72:75]
	v_mfma_f32_16x16x32_bf16 v[116:119], v[168:171], v[184:187], v[116:119]
	v_mfma_f32_16x16x32_bf16 v[112:115], v[176:179], v[184:187], v[112:115]
	v_mfma_f32_16x16x32_bf16 v[100:103], v[168:171], v[192:195], v[100:103]
	v_mfma_f32_16x16x32_bf16 v[96:99], v[176:179], v[192:195], v[96:99]
	v_mfma_f32_16x16x32_bf16 v[84:87], v[168:171], v[200:203], v[84:87]
	v_mfma_f32_16x16x32_bf16 v[80:83], v[176:179], v[200:203], v[80:83]
	v_mfma_f32_16x16x32_bf16 v[68:71], v[168:171], v[208:211], v[68:71]
	v_mfma_f32_16x16x32_bf16 v[64:67], v[176:179], v[208:211], v[64:67]
	v_mfma_f32_16x16x32_bf16 v[116:119], v[172:175], v[188:191], v[116:119]
	v_mfma_f32_16x16x32_bf16 v[112:115], v[180:183], v[188:191], v[112:115]
	v_mfma_f32_16x16x32_bf16 v[100:103], v[172:175], v[196:199], v[100:103]
	v_mfma_f32_16x16x32_bf16 v[96:99], v[180:183], v[196:199], v[96:99]
	v_mfma_f32_16x16x32_bf16 v[84:87], v[172:175], v[204:207], v[84:87]
	v_mfma_f32_16x16x32_bf16 v[80:83], v[180:183], v[204:207], v[80:83]
	v_mfma_f32_16x16x32_bf16 v[68:71], v[172:175], v[212:215], v[68:71]
	v_mfma_f32_16x16x32_bf16 v[64:67], v[180:183], v[212:215], v[64:67]
	s_setprio 0
	s_barrier
	s_add_u32 s98, s40, s16
	s_addc_u32 s99, s41, s17
	s_add_i32 s42, s64, s35
	s_mov_b32 m0, s42
	ds_read_b128 v[184:187], v150 offset:49152
	ds_read_b128 v[188:191], v150 offset:50176
	ds_read_b128 v[192:195], v150 offset:51200
	ds_read_b128 v[196:199], v150 offset:52224
	ds_read_b128 v[200:203], v150 offset:53248
	ds_read_b128 v[204:207], v150 offset:54272
	ds_read_b128 v[208:211], v150 offset:55296
	ds_read_b128 v[212:215], v150 offset:56320
	global_load_lds_dwordx4 v130, s[98:99]
	s_add_i32 m0, s42, 0x2000
	s_add_u32 s40, s40, 0x100080
	v_lshl_add_u64 v[216:217], v[218:219], 0, s[16:17]
	s_addc_u32 s41, s41, 0
	s_add_i32 s42, s65, s35
	global_load_lds_dwordx4 v[216:217], off
	s_mov_b32 m0, s42
	s_nop 0
	global_load_lds_dwordx4 v130, s[40:41]
	s_add_i32 m0, s42, 0x2000
	s_nop 0
	global_load_lds_dwordx4 v134, s[40:41]
	s_mov_b32 m0, s48
	s_nop 0
	global_load_lds_dwordx4 v128, s[38:39]
	s_mov_b32 m0, s49
	s_nop 0
	global_load_lds_dwordx4 v132, s[38:39]
	s_waitcnt vmcnt(8)
	s_waitcnt lgkmcnt(0)
	s_barrier
	s_setprio 1
	v_mfma_f32_16x16x32_bf16 v[60:63], v[152:155], v[184:187], v[60:63]
	v_mfma_f32_16x16x32_bf16 v[56:59], v[160:163], v[184:187], v[56:59]
	v_mfma_f32_16x16x32_bf16 v[44:47], v[152:155], v[192:195], v[44:47]
	v_mfma_f32_16x16x32_bf16 v[40:43], v[160:163], v[192:195], v[40:43]
	v_mfma_f32_16x16x32_bf16 v[28:31], v[152:155], v[200:203], v[28:31]
	v_mfma_f32_16x16x32_bf16 v[24:27], v[160:163], v[200:203], v[24:27]
	v_mfma_f32_16x16x32_bf16 v[12:15], v[152:155], v[208:211], v[12:15]
	v_mfma_f32_16x16x32_bf16 v[8:11], v[160:163], v[208:211], v[8:11]
	v_mfma_f32_16x16x32_bf16 v[60:63], v[156:159], v[188:191], v[60:63]
	v_mfma_f32_16x16x32_bf16 v[56:59], v[164:167], v[188:191], v[56:59]
	v_mfma_f32_16x16x32_bf16 v[44:47], v[156:159], v[196:199], v[44:47]
	v_mfma_f32_16x16x32_bf16 v[40:43], v[164:167], v[196:199], v[40:43]
	v_mfma_f32_16x16x32_bf16 v[28:31], v[156:159], v[204:207], v[28:31]
	v_mfma_f32_16x16x32_bf16 v[24:27], v[164:167], v[204:207], v[24:27]
	v_mfma_f32_16x16x32_bf16 v[12:15], v[156:159], v[212:215], v[12:15]
	v_mfma_f32_16x16x32_bf16 v[8:11], v[164:167], v[212:215], v[8:11]
	v_mfma_f32_16x16x32_bf16 v[52:55], v[168:171], v[184:187], v[52:55]
	v_mfma_f32_16x16x32_bf16 v[48:51], v[176:179], v[184:187], v[48:51]
	v_mfma_f32_16x16x32_bf16 v[36:39], v[168:171], v[192:195], v[36:39]
	v_mfma_f32_16x16x32_bf16 v[32:35], v[176:179], v[192:195], v[32:35]
	v_mfma_f32_16x16x32_bf16 v[20:23], v[168:171], v[200:203], v[20:23]
	v_mfma_f32_16x16x32_bf16 v[16:19], v[176:179], v[200:203], v[16:19]
	v_mfma_f32_16x16x32_bf16 v[4:7], v[168:171], v[208:211], v[4:7]
	v_mfma_f32_16x16x32_bf16 v[0:3], v[176:179], v[208:211], v[0:3]
	v_mfma_f32_16x16x32_bf16 v[52:55], v[172:175], v[188:191], v[52:55]
	v_mfma_f32_16x16x32_bf16 v[48:51], v[180:183], v[188:191], v[48:51]
	v_mfma_f32_16x16x32_bf16 v[36:39], v[172:175], v[196:199], v[36:39]
	v_mfma_f32_16x16x32_bf16 v[32:35], v[180:183], v[196:199], v[32:35]
	v_mfma_f32_16x16x32_bf16 v[20:23], v[172:175], v[204:207], v[20:23]
	v_mfma_f32_16x16x32_bf16 v[16:19], v[180:183], v[204:207], v[16:19]
	v_mfma_f32_16x16x32_bf16 v[4:7], v[172:175], v[212:215], v[4:7]
	v_mfma_f32_16x16x32_bf16 v[0:3], v[180:183], v[212:215], v[0:3]
	s_setprio 0
	s_barrier
	s_add_i32 s63, s63, 2
	s_add_u32 s61, s61, 0x100
	s_addc_u32 s62, s62, 0
	s_add_u32 s36, s36, 0x10000
	s_addc_u32 s37, s37, 0
	v_lshl_add_u64 v[146:147], v[146:147], 0, s[18:19]
	s_cmp_gt_u32 s63, 61
	v_lshl_add_u64 v[144:145], v[144:145], 0, s[18:19]
	s_cbranch_scc0 .LBB0_615
	s_andn2_b64 vcc, exec, s[4:5]
	s_cbranch_vccnz .LBB0_607
	v_mov_b32_e32 v0, 0
	s_mov_b32 s8, s20
	s_mov_b32 s6, s22
	s_mov_b64 s[10:11], s[28:29]
	s_mov_b64 s[12:13], s[26:27]
	s_mov_b32 s50, s57
	v_mov_b32_e32 v1, v0
	v_mov_b32_e32 v2, v0
	v_mov_b32_e32 v3, v0
	v_mov_b32_e32 v4, v0
	v_mov_b32_e32 v5, v0
	v_mov_b32_e32 v6, v0
	v_mov_b32_e32 v7, v0
	v_mov_b32_e32 v16, v0
	v_mov_b32_e32 v17, v0
	v_mov_b32_e32 v18, v0
	v_mov_b32_e32 v19, v0
	v_mov_b32_e32 v20, v0
	v_mov_b32_e32 v21, v0
	v_mov_b32_e32 v22, v0
	v_mov_b32_e32 v23, v0
	v_mov_b32_e32 v32, v0
	v_mov_b32_e32 v33, v0
	v_mov_b32_e32 v34, v0
	v_mov_b32_e32 v35, v0
	v_mov_b32_e32 v36, v0
	v_mov_b32_e32 v37, v0
	v_mov_b32_e32 v38, v0
	v_mov_b32_e32 v39, v0
	v_mov_b32_e32 v48, v0
	v_mov_b32_e32 v49, v0
	v_mov_b32_e32 v50, v0
	v_mov_b32_e32 v51, v0
	v_mov_b32_e32 v52, v0
	v_mov_b32_e32 v53, v0
	v_mov_b32_e32 v54, v0
	v_mov_b32_e32 v55, v0
	v_mov_b32_e32 v8, v0
	v_mov_b32_e32 v9, v0
	v_mov_b32_e32 v10, v0
	v_mov_b32_e32 v11, v0
	v_mov_b32_e32 v12, v0
	v_mov_b32_e32 v13, v0
	v_mov_b32_e32 v14, v0
	v_mov_b32_e32 v15, v0
	v_mov_b32_e32 v24, v0
	v_mov_b32_e32 v25, v0
	v_mov_b32_e32 v26, v0
	v_mov_b32_e32 v27, v0
	v_mov_b32_e32 v28, v0
	v_mov_b32_e32 v29, v0
	v_mov_b32_e32 v30, v0
	v_mov_b32_e32 v31, v0
	v_mov_b32_e32 v40, v0
	v_mov_b32_e32 v41, v0
	v_mov_b32_e32 v42, v0
	v_mov_b32_e32 v43, v0
	v_mov_b32_e32 v44, v0
	v_mov_b32_e32 v45, v0
	v_mov_b32_e32 v46, v0
	v_mov_b32_e32 v47, v0
	v_mov_b32_e32 v56, v0
	v_mov_b32_e32 v57, v0
	v_mov_b32_e32 v58, v0
	v_mov_b32_e32 v59, v0
	v_mov_b32_e32 v60, v0
	v_mov_b32_e32 v61, v0
	v_mov_b32_e32 v62, v0
	v_mov_b32_e32 v63, v0
	v_mov_b32_e32 v64, v0
	v_mov_b32_e32 v65, v0
	v_mov_b32_e32 v66, v0
	v_mov_b32_e32 v67, v0
	v_mov_b32_e32 v68, v0
	v_mov_b32_e32 v69, v0
	v_mov_b32_e32 v70, v0
	v_mov_b32_e32 v71, v0
	v_mov_b32_e32 v80, v0
	v_mov_b32_e32 v81, v0
	v_mov_b32_e32 v82, v0
	v_mov_b32_e32 v83, v0
	v_mov_b32_e32 v84, v0
	v_mov_b32_e32 v85, v0
	v_mov_b32_e32 v86, v0
	v_mov_b32_e32 v87, v0
	v_mov_b32_e32 v96, v0
	v_mov_b32_e32 v97, v0
	v_mov_b32_e32 v98, v0
	v_mov_b32_e32 v99, v0
	v_mov_b32_e32 v100, v0
	v_mov_b32_e32 v101, v0
	v_mov_b32_e32 v102, v0
	v_mov_b32_e32 v103, v0
	v_mov_b32_e32 v112, v0
	v_mov_b32_e32 v113, v0
	v_mov_b32_e32 v114, v0
	v_mov_b32_e32 v115, v0
	v_mov_b32_e32 v116, v0
	v_mov_b32_e32 v117, v0
	v_mov_b32_e32 v118, v0
	v_mov_b32_e32 v119, v0
	v_mov_b32_e32 v72, v0
	v_mov_b32_e32 v73, v0
	v_mov_b32_e32 v74, v0
	v_mov_b32_e32 v75, v0
	v_mov_b32_e32 v76, v0
	v_mov_b32_e32 v77, v0
	v_mov_b32_e32 v78, v0
	v_mov_b32_e32 v79, v0
	v_mov_b32_e32 v88, v0
	v_mov_b32_e32 v89, v0
	v_mov_b32_e32 v90, v0
	v_mov_b32_e32 v91, v0
	v_mov_b32_e32 v92, v0
	v_mov_b32_e32 v93, v0
	v_mov_b32_e32 v94, v0
	v_mov_b32_e32 v95, v0
	v_mov_b32_e32 v104, v0
	v_mov_b32_e32 v105, v0
	v_mov_b32_e32 v106, v0
	v_mov_b32_e32 v107, v0
	v_mov_b32_e32 v108, v0
	v_mov_b32_e32 v109, v0
	v_mov_b32_e32 v110, v0
	v_mov_b32_e32 v111, v0
	v_mov_b32_e32 v120, v0
	v_mov_b32_e32 v121, v0
	v_mov_b32_e32 v122, v0
	v_mov_b32_e32 v123, v0
	v_mov_b32_e32 v124, v0
	v_mov_b32_e32 v125, v0
	v_mov_b32_e32 v126, v0
	v_mov_b32_e32 v127, v0
	s_branch .LBB0_607

.LBB0_647:
	s_and_b32 s10, s15, 0xff
	s_mov_b64 s[8:9], -1
	s_cmp_lg_u32 s10, 0
	s_mov_b64 s[12:13], -1
	s_cbranch_scc0 .LBB0_650
	s_and_b64 vcc, exec, s[12:13]
	s_cbranch_vccz .LBB0_646
